# V fragment lookahead 7 instead of 5 (the LDS queue no longer carries staging writes)
# baseline (speedup 1.0000x reference)
; __device__ __forceinline__ void finishSM(f32x16& p0, f32x16& p1, float alpha, float& l_reg, bf16x8& pa0, bf16x8& pa1, bf16x8& pa2, bf16x8& pa3) {
; #pragma unroll
;   for (int r = 0; r < 16; ++r) p1[r] = __builtin_amdgcn_exp2f(p1[r]);
;   float ps = 0;
; #pragma unroll
;   for (int r = 0; r < 16; ++r) ps += p0[r];
; #pragma unroll
;   for (int r = 0; r < 16; ++r) ps += p1[r];
;   { auto rr = __builtin_amdgcn_permlane32_swap(__float_as_uint(ps), __float_as_uint(ps), false, false);
;     ps = __uint_as_float(rr[0]) + __uint_as_float(rr[1]); }
;   l_reg = l_reg * alpha + ps;
;     ...
;   PK4(p0, 0, pa0); PK4(p0, 8, pa1); PK4(p1, 0, pa2); PK4(p1, 8, pa3);
;     ...
; }
; __device__ __forceinline__ void qkt(f32x16& p0, f32x16& p1, const bf16* Ks, const bf16x8* qr, int r32, int hi) {
;   p0 = f32x16{}; p1 = f32x16{};
; #pragma unroll
;   for (int d0 = 0; d0 < 8; ++d0) { int cb = (d0 * 16 + hi * 8) * 2;
;     bf16x8 b0 = *reinterpret_cast<const bf16x8*>((const char*)Ks + KSWZ(r32, cb));
;     bf16x8 b1 = *reinterpret_cast<const bf16x8*>((const char*)Ks + KSWZ(32 + r32, cb));
;     p0 = __builtin_amdgcn_mfma_f32_32x32x16_bf16(b0, qr[d0], p0, 0, 0, 0);
;     p1 = __builtin_amdgcn_mfma_f32_32x32x16_bf16(b1, qr[d0], p1, 0, 0, 0); }
; }
; __device__ __forceinline__ int v_st(int k, int c) { const int kk = (k & ~0xC) | ((k & 4) << 1) | ((k & 8) >> 1); return ((kk >> 3) * 4 + (c >> 5)) * 512 + ((kk & 7) * 32 + (c & 31)) * 2; }
; __device__ __forceinline__ int v_rd_base(int lane) { return ((lane & 3) << 3) | (((lane >> 2) & 3) << 6) | (((lane >> 4) & 1) << 5) | (((lane >> 5) & 1) << 8); }
; template <int OFF> __device__ __forceinline__ s16x4 tr_read(int vb) {
;   s16x4 r; asm volatile("ds_read_b64_tr_b16 %0, %1 offset:%2" : "=&v"(r) : "v"(vb), "i"(OFF) : "memory"); return r;
; }
; template <int D0> __device__ __forceinline__ void pv_one(f32x16& od, int vb, bf16x8 pa0, bf16x8 pa1, bf16x8 pa2, bf16x8 pa3) {
;   const s16x4 l0 = tr_read<v_rd_off(D0, 0, 0)>(vb), h0 = tr_read<v_rd_off(D0, 0, 1)>(vb), l1 = tr_read<v_rd_off(D0, 1, 0)>(vb), h1 = tr_read<v_rd_off(D0, 1, 1)>(vb);
;   const s16x4 l2 = tr_read<v_rd_off(D0, 2, 0)>(vb), h2 = tr_read<v_rd_off(D0, 2, 1)>(vb), l3 = tr_read<v_rd_off(D0, 3, 0)>(vb), h3 = tr_read<v_rd_off(D0, 3, 1)>(vb);
;   asm volatile("s_waitcnt lgkmcnt(0)" ::: "memory"); SBAR();
;     ...
;   od = __builtin_amdgcn_mfma_f32_32x32x16_bf16(pa0, PK(l0, h0), od, 0, 0, 0);
.Lprio_done:
.Ldense_loop:
	s_waitcnt lgkmcnt(7)
	v_mfma_f32_16x16x32_bf16 v[128:131], v[200:203], v[96:99], 0
	v_add_f32_e32 v169, v169, v64
	s_add_i32 m0, s32, 0x0
	s_nop 0
	global_load_lds_dwordx4 v183, s[98:99]
	v_mfma_f32_16x16x32_bf16 v[132:135], v[200:203], v[112:115], 0
	ds_read_b128 v[200:203], v174 offset:16384
	v_add_f32_e32 v169, v169, v65
	v_cvt_pk_bf16_f32 v184, v64, v65
	s_waitcnt lgkmcnt(7)
	v_mfma_f32_16x16x32_bf16 v[136:139], v[204:207], v[96:99], 0
	v_add_f32_e32 v169, v169, v66
	v_mfma_f32_16x16x32_bf16 v[140:143], v[204:207], v[112:115], 0
	ds_read_b128 v[204:207], v174 offset:20480
	v_add_f32_e32 v169, v169, v67
	v_cvt_pk_bf16_f32 v185, v66, v67
	s_waitcnt lgkmcnt(7)
	v_mfma_f32_16x16x32_bf16 v[144:147], v[208:211], v[96:99], 0
	v_add_f32_e32 v222, v222, v68
	s_add_i32 m0, s32, 0x2000
	s_nop 0
	global_load_lds_dwordx4 v183, s[100:101]
	s_add_u32 s98, s98, 0x150000
	s_addc_u32 s99, s99, 0
	s_add_u32 s100, s100, 0x150000
	s_addc_u32 s101, s101, 0
	v_mfma_f32_16x16x32_bf16 v[148:151], v[208:211], v[112:115], 0
	ds_read_b128 v[208:211], v174 offset:24576
	v_add_f32_e32 v222, v222, v69
	v_cvt_pk_bf16_f32 v186, v72, v73
	s_waitcnt lgkmcnt(7)
	v_mfma_f32_16x16x32_bf16 v[152:155], v[212:215], v[96:99], 0
	v_add_f32_e32 v222, v222, v70
	v_mfma_f32_16x16x32_bf16 v[156:159], v[212:215], v[112:115], 0
	ds_read_b128 v[212:215], v174 offset:28672
	v_add_f32_e32 v222, v222, v71
	v_cvt_pk_bf16_f32 v187, v74, v75
	s_waitcnt lgkmcnt(7)
	v_mfma_f32_16x16x32_bf16 v[128:131], v[230:233], v[100:103], v[128:131]
	v_add_f32_e32 v169, v169, v72
	s_add_i32 m0, s32, 0x18000
	s_nop 0
	global_load_lds_dwordx4 v181, s[0:1]
	v_mfma_f32_16x16x32_bf16 v[132:135], v[230:233], v[116:119], v[132:135]
	ds_read_b128 v[230:233], v175 offset:16384
	v_add_f32_e32 v169, v169, v73
	v_cvt_pk_bf16_f32 v188, v80, v81
	s_waitcnt lgkmcnt(7)
	v_mfma_f32_16x16x32_bf16 v[136:139], v[234:237], v[100:103], v[136:139]
	v_add_f32_e32 v169, v169, v74
	v_mfma_f32_16x16x32_bf16 v[140:143], v[234:237], v[116:119], v[140:143]
	ds_read_b128 v[234:237], v175 offset:20480
	v_add_f32_e32 v169, v169, v75
	v_cvt_pk_bf16_f32 v189, v82, v83
	s_waitcnt lgkmcnt(7)
	v_mfma_f32_16x16x32_bf16 v[144:147], v[238:241], v[100:103], v[144:147]
	v_add_f32_e32 v222, v222, v76
	s_add_i32 m0, s32, 0x1a000
	s_nop 0
	global_load_lds_dwordx4 v181, s[4:5]
	s_add_u32 s0, s0, 0x150000
	s_addc_u32 s1, s1, 0
	s_add_u32 s4, s4, 0x150000
	s_addc_u32 s5, s5, 0
	v_mfma_f32_16x16x32_bf16 v[148:151], v[238:241], v[116:119], v[148:151]
	ds_read_b128 v[238:241], v175 offset:24576
	v_add_f32_e32 v222, v222, v77
	v_cvt_pk_bf16_f32 v190, v88, v89
	s_waitcnt lgkmcnt(7)
	v_mfma_f32_16x16x32_bf16 v[152:155], v[242:245], v[100:103], v[152:155]
	v_add_f32_e32 v222, v222, v78
	v_mfma_f32_16x16x32_bf16 v[156:159], v[242:245], v[116:119], v[156:159]
	ds_read_b128 v[242:245], v175 offset:28672
	v_add_f32_e32 v222, v222, v79
	v_cvt_pk_bf16_f32 v191, v90, v91
	s_waitcnt lgkmcnt(7)
	v_mfma_f32_16x16x32_bf16 v[128:131], v[200:203], v[104:107], v[128:131]
	v_add_f32_e32 v169, v169, v80
	v_mfma_f32_16x16x32_bf16 v[132:135], v[200:203], v[120:123], v[132:135]
	v_add_f32_e32 v169, v169, v81
	v_cvt_pk_bf16_f32 v192, v68, v69
	s_waitcnt lgkmcnt(6)
	v_mfma_f32_16x16x32_bf16 v[136:139], v[204:207], v[104:107], v[136:139]
	ds_read_b64_tr_b16 v[200:201], v176 offset:0
	ds_read_b64_tr_b16 v[202:203], v176 offset:4096
	v_add_f32_e32 v169, v169, v82
	v_mfma_f32_16x16x32_bf16 v[140:143], v[204:207], v[120:123], v[140:143]
	v_add_f32_e32 v169, v169, v83
	v_cvt_pk_bf16_f32 v193, v70, v71
	s_waitcnt lgkmcnt(7)
	v_mfma_f32_16x16x32_bf16 v[144:147], v[208:211], v[104:107], v[144:147]
	ds_read_b64_tr_b16 v[204:205], v177 offset:0
	ds_read_b64_tr_b16 v[206:207], v177 offset:4096
	v_add_f32_e32 v222, v222, v84
	v_mfma_f32_16x16x32_bf16 v[148:151], v[208:211], v[120:123], v[148:151]
	v_add_f32_e32 v222, v222, v85
	v_cvt_pk_bf16_f32 v194, v76, v77
	s_waitcnt lgkmcnt(8)
	v_mfma_f32_16x16x32_bf16 v[152:155], v[212:215], v[104:107], v[152:155]
	ds_read_b64_tr_b16 v[208:209], v178 offset:0
	ds_read_b64_tr_b16 v[210:211], v178 offset:4096
	v_add_f32_e32 v222, v222, v86
	v_mfma_f32_16x16x32_bf16 v[156:159], v[212:215], v[120:123], v[156:159]
	v_add_f32_e32 v222, v222, v87
	v_cvt_pk_bf16_f32 v195, v78, v79
	s_waitcnt lgkmcnt(9)
	v_mfma_f32_16x16x32_bf16 v[128:131], v[230:233], v[108:111], v[128:131]
	ds_read_b64_tr_b16 v[212:213], v179 offset:0
	ds_read_b64_tr_b16 v[214:215], v179 offset:4096
	v_add_f32_e32 v169, v169, v88
	v_mfma_f32_16x16x32_bf16 v[132:135], v[230:233], v[124:127], v[132:135]
	v_add_f32_e32 v169, v169, v89
	v_cvt_pk_bf16_f32 v196, v84, v85
	s_waitcnt lgkmcnt(10)
	v_mfma_f32_16x16x32_bf16 v[136:139], v[234:237], v[108:111], v[136:139]
	ds_read_b64_tr_b16 v[230:231], v180 offset:0
	ds_read_b64_tr_b16 v[232:233], v180 offset:4096
	v_add_f32_e32 v169, v169, v90
	v_mfma_f32_16x16x32_bf16 v[140:143], v[234:237], v[124:127], v[140:143]
	v_add_f32_e32 v169, v169, v91
	v_cvt_pk_bf16_f32 v197, v86, v87
	s_waitcnt lgkmcnt(11)
	v_mfma_f32_16x16x32_bf16 v[144:147], v[238:241], v[108:111], v[144:147]
	ds_read_b64_tr_b16 v[234:235], v182 offset:0
	ds_read_b64_tr_b16 v[236:237], v182 offset:4096
	v_add_f32_e32 v222, v222, v92
	v_mfma_f32_16x16x32_bf16 v[148:151], v[238:241], v[124:127], v[148:151]
	v_add_f32_e32 v222, v222, v93
	v_cvt_pk_bf16_f32 v198, v92, v93
	s_waitcnt lgkmcnt(12)
	v_mfma_f32_16x16x32_bf16 v[152:155], v[242:245], v[108:111], v[152:155]
	ds_read_b64_tr_b16 v[238:239], v216 offset:0
	ds_read_b64_tr_b16 v[240:241], v216 offset:4096
	v_add_f32_e32 v222, v222, v94
	v_mfma_f32_16x16x32_bf16 v[156:159], v[242:245], v[124:127], v[156:159]
	v_add_f32_e32 v222, v222, v95
	v_cvt_pk_bf16_f32 v199, v94, v95
	s_waitcnt lgkmcnt(12)
; __device__ __forceinline__ void finishSM(f32x16& p0, f32x16& p1, float alpha, float& l_reg, bf16x8& pa0, bf16x8& pa1, bf16x8& pa2, bf16x8& pa3) {
; #pragma unroll
;   for (int r = 0; r < 16; ++r) p1[r] = __builtin_amdgcn_exp2f(p1[r]);
;   float ps = 0;
; #pragma unroll
;   for (int r = 0; r < 16; ++r) ps += p0[r];
; #pragma unroll
;   for (int r = 0; r < 16; ++r) ps += p1[r];
;   { auto rr = __builtin_amdgcn_permlane32_swap(__float_as_uint(ps), __float_as_uint(ps), false, false);
;     ps = __uint_as_float(rr[0]) + __uint_as_float(rr[1]); }
;   l_reg = l_reg * alpha + ps;
;     ...
;   PK4(p0, 0, pa0); PK4(p0, 8, pa1); PK4(p1, 0, pa2); PK4(p1, 8, pa3);
;     ...
; }
; __device__ __forceinline__ void qkt(f32x16& p0, f32x16& p1, const bf16* Ks, const bf16x8* qr, int r32, int hi) {
;   p0 = f32x16{}; p1 = f32x16{};
; #pragma unroll
;   for (int d0 = 0; d0 < 8; ++d0) { int cb = (d0 * 16 + hi * 8) * 2;
;     bf16x8 b0 = *reinterpret_cast<const bf16x8*>((const char*)Ks + KSWZ(r32, cb));
;     bf16x8 b1 = *reinterpret_cast<const bf16x8*>((const char*)Ks + KSWZ(32 + r32, cb));
;     p0 = __builtin_amdgcn_mfma_f32_32x32x16_bf16(b0, qr[d0], p0, 0, 0, 0);
;     p1 = __builtin_amdgcn_mfma_f32_32x32x16_bf16(b1, qr[d0], p1, 0, 0, 0); }
; }
; __device__ __forceinline__ int v_st(int k, int c) { const int kk = (k & ~0xC) | ((k & 4) << 1) | ((k & 8) >> 1); return ((kk >> 3) * 4 + (c >> 5)) * 512 + ((kk & 7) * 32 + (c & 31)) * 2; }
; __device__ __forceinline__ int v_rd_base(int lane) { return ((lane & 3) << 3) | (((lane >> 2) & 3) << 6) | (((lane >> 4) & 1) << 5) | (((lane >> 5) & 1) << 8); }
; template <int OFF> __device__ __forceinline__ s16x4 tr_read(int vb) {
;   s16x4 r; asm volatile("ds_read_b64_tr_b16 %0, %1 offset:%2" : "=&v"(r) : "v"(vb), "i"(OFF) : "memory"); return r;
; }
; template <int D0> __device__ __forceinline__ void pv_one(f32x16& od, int vb, bf16x8 pa0, bf16x8 pa1, bf16x8 pa2, bf16x8 pa3) {
;   const s16x4 l0 = tr_read<v_rd_off(D0, 0, 0)>(vb), h0 = tr_read<v_rd_off(D0, 0, 1)>(vb), l1 = tr_read<v_rd_off(D0, 1, 0)>(vb), h1 = tr_read<v_rd_off(D0, 1, 1)>(vb);
;   const s16x4 l2 = tr_read<v_rd_off(D0, 2, 0)>(vb), h2 = tr_read<v_rd_off(D0, 2, 1)>(vb), l3 = tr_read<v_rd_off(D0, 3, 0)>(vb), h3 = tr_read<v_rd_off(D0, 3, 1)>(vb);
;   asm volatile("s_waitcnt lgkmcnt(0)" ::: "memory"); SBAR();
;     ...
;   od = __builtin_amdgcn_mfma_f32_32x32x16_bf16(pa0, PK(l0, h0), od, 0, 0, 0);
	v_mfma_f32_16x16x32_bf16 v[0:3], v[200:203], v[184:187], v[0:3]
	v_exp_f32_e32 v128, v128
	v_mfma_f32_16x16x32_bf16 v[32:35], v[200:203], v[192:195], v[32:35]
	ds_read_b64_tr_b16 v[242:243], v217 offset:0
	ds_read_b64_tr_b16 v[244:245], v217 offset:4096
	v_exp_f32_e32 v129, v129
	s_waitcnt lgkmcnt(12)
	v_mfma_f32_16x16x32_bf16 v[4:7], v[204:207], v[184:187], v[4:7]
	v_exp_f32_e32 v130, v130
	v_mfma_f32_16x16x32_bf16 v[36:39], v[204:207], v[192:195], v[36:39]
	ds_read_b64_tr_b16 v[200:201], v176 offset:8192
	ds_read_b64_tr_b16 v[202:203], v176 offset:12288
	v_exp_f32_e32 v131, v131
	s_waitcnt lgkmcnt(12)
	v_mfma_f32_16x16x32_bf16 v[8:11], v[208:211], v[184:187], v[8:11]
	v_exp_f32_e32 v132, v132
	v_mfma_f32_16x16x32_bf16 v[40:43], v[208:211], v[192:195], v[40:43]
	ds_read_b64_tr_b16 v[204:205], v177 offset:8192
	ds_read_b64_tr_b16 v[206:207], v177 offset:12288
	v_exp_f32_e32 v133, v133
	s_waitcnt lgkmcnt(12)
	v_mfma_f32_16x16x32_bf16 v[12:15], v[212:215], v[184:187], v[12:15]
	v_exp_f32_e32 v134, v134
	v_mfma_f32_16x16x32_bf16 v[44:47], v[212:215], v[192:195], v[44:47]
	ds_read_b64_tr_b16 v[208:209], v178 offset:8192
	ds_read_b64_tr_b16 v[210:211], v178 offset:12288
	v_exp_f32_e32 v135, v135
	s_waitcnt lgkmcnt(12)
	v_mfma_f32_16x16x32_bf16 v[16:19], v[230:233], v[184:187], v[16:19]
	v_exp_f32_e32 v136, v136
	v_mfma_f32_16x16x32_bf16 v[48:51], v[230:233], v[192:195], v[48:51]
	ds_read_b64_tr_b16 v[212:213], v179 offset:8192
	ds_read_b64_tr_b16 v[214:215], v179 offset:12288
	v_exp_f32_e32 v137, v137
	s_waitcnt lgkmcnt(12)
	v_mfma_f32_16x16x32_bf16 v[20:23], v[234:237], v[184:187], v[20:23]
	v_exp_f32_e32 v138, v138
	v_mfma_f32_16x16x32_bf16 v[52:55], v[234:237], v[192:195], v[52:55]
	ds_read_b64_tr_b16 v[230:231], v180 offset:8192
	ds_read_b64_tr_b16 v[232:233], v180 offset:12288
	v_exp_f32_e32 v139, v139
	s_waitcnt lgkmcnt(12)
	v_mfma_f32_16x16x32_bf16 v[24:27], v[238:241], v[184:187], v[24:27]
	v_exp_f32_e32 v140, v140
	v_mfma_f32_16x16x32_bf16 v[56:59], v[238:241], v[192:195], v[56:59]
	ds_read_b64_tr_b16 v[234:235], v182 offset:8192
	ds_read_b64_tr_b16 v[236:237], v182 offset:12288
	v_exp_f32_e32 v141, v141
	s_waitcnt lgkmcnt(12)
	v_mfma_f32_16x16x32_bf16 v[28:31], v[242:245], v[184:187], v[28:31]
	v_exp_f32_e32 v142, v142
	v_mfma_f32_16x16x32_bf16 v[60:63], v[242:245], v[192:195], v[60:63]
	ds_read_b64_tr_b16 v[238:239], v216 offset:8192
	ds_read_b64_tr_b16 v[240:241], v216 offset:12288
	v_exp_f32_e32 v143, v143
	s_waitcnt lgkmcnt(12)
	v_mfma_f32_16x16x32_bf16 v[0:3], v[200:203], v[188:191], v[0:3]
	v_exp_f32_e32 v144, v144
	v_mfma_f32_16x16x32_bf16 v[32:35], v[200:203], v[196:199], v[32:35]
	ds_read_b64_tr_b16 v[242:243], v217 offset:8192
	ds_read_b64_tr_b16 v[244:245], v217 offset:12288
	ds_read_b128 v[200:203], v172 offset:32768
	v_exp_f32_e32 v145, v145
	s_waitcnt lgkmcnt(13)
	v_mfma_f32_16x16x32_bf16 v[4:7], v[204:207], v[188:191], v[4:7]
	v_exp_f32_e32 v146, v146
	v_mfma_f32_16x16x32_bf16 v[36:39], v[204:207], v[196:199], v[36:39]
	ds_read_b128 v[204:207], v172 offset:36864
	v_exp_f32_e32 v147, v147
	s_waitcnt lgkmcnt(12)
	v_mfma_f32_16x16x32_bf16 v[8:11], v[208:211], v[188:191], v[8:11]
	v_exp_f32_e32 v148, v148
	v_mfma_f32_16x16x32_bf16 v[40:43], v[208:211], v[196:199], v[40:43]
	ds_read_b128 v[208:211], v172 offset:40960
	v_exp_f32_e32 v149, v149
	s_waitcnt lgkmcnt(11)
	v_mfma_f32_16x16x32_bf16 v[12:15], v[212:215], v[188:191], v[12:15]
	v_exp_f32_e32 v150, v150
	v_mfma_f32_16x16x32_bf16 v[44:47], v[212:215], v[196:199], v[44:47]
	ds_read_b128 v[212:215], v172 offset:45056
	v_exp_f32_e32 v151, v151
	s_waitcnt lgkmcnt(10)
	v_mfma_f32_16x16x32_bf16 v[16:19], v[230:233], v[188:191], v[16:19]
	v_exp_f32_e32 v152, v152
	v_mfma_f32_16x16x32_bf16 v[48:51], v[230:233], v[196:199], v[48:51]
	ds_read_b128 v[230:233], v173 offset:32768
	v_exp_f32_e32 v153, v153
	s_waitcnt lgkmcnt(9)
	v_mfma_f32_16x16x32_bf16 v[20:23], v[234:237], v[188:191], v[20:23]
	v_exp_f32_e32 v154, v154
	v_mfma_f32_16x16x32_bf16 v[52:55], v[234:237], v[196:199], v[52:55]
	ds_read_b128 v[234:237], v173 offset:36864
	v_exp_f32_e32 v155, v155
	s_waitcnt lgkmcnt(8)
	v_mfma_f32_16x16x32_bf16 v[24:27], v[238:241], v[188:191], v[24:27]
	v_exp_f32_e32 v156, v156
	v_mfma_f32_16x16x32_bf16 v[56:59], v[238:241], v[196:199], v[56:59]
	ds_read_b128 v[238:241], v173 offset:40960
	v_exp_f32_e32 v157, v157
	s_waitcnt lgkmcnt(7)
	v_mfma_f32_16x16x32_bf16 v[28:31], v[242:245], v[188:191], v[28:31]
	v_exp_f32_e32 v158, v158
	v_mfma_f32_16x16x32_bf16 v[60:63], v[242:245], v[196:199], v[60:63]
	ds_read_b128 v[242:245], v173 offset:45056
	v_exp_f32_e32 v159, v159
	s_waitcnt vmcnt(4)
	s_barrier
; __device__ __forceinline__ void finishSM(f32x16& p0, f32x16& p1, float alpha, float& l_reg, bf16x8& pa0, bf16x8& pa1, bf16x8& pa2, bf16x8& pa3) {
; #pragma unroll
;   for (int r = 0; r < 16; ++r) p1[r] = __builtin_amdgcn_exp2f(p1[r]);
;   float ps = 0;
; #pragma unroll
;   for (int r = 0; r < 16; ++r) ps += p0[r];
; #pragma unroll
;   for (int r = 0; r < 16; ++r) ps += p1[r];
;   { auto rr = __builtin_amdgcn_permlane32_swap(__float_as_uint(ps), __float_as_uint(ps), false, false);
;     ps = __uint_as_float(rr[0]) + __uint_as_float(rr[1]); }
;   l_reg = l_reg * alpha + ps;
;     ...
;   PK4(p0, 0, pa0); PK4(p0, 8, pa1); PK4(p1, 0, pa2); PK4(p1, 8, pa3);
;     ...
; }
; __device__ __forceinline__ void qkt(f32x16& p0, f32x16& p1, const bf16* Ks, const bf16x8* qr, int r32, int hi) {
;   p0 = f32x16{}; p1 = f32x16{};
; #pragma unroll
;   for (int d0 = 0; d0 < 8; ++d0) { int cb = (d0 * 16 + hi * 8) * 2;
;     bf16x8 b0 = *reinterpret_cast<const bf16x8*>((const char*)Ks + KSWZ(r32, cb));
;     bf16x8 b1 = *reinterpret_cast<const bf16x8*>((const char*)Ks + KSWZ(32 + r32, cb));
;     p0 = __builtin_amdgcn_mfma_f32_32x32x16_bf16(b0, qr[d0], p0, 0, 0, 0);
;     p1 = __builtin_amdgcn_mfma_f32_32x32x16_bf16(b1, qr[d0], p1, 0, 0, 0); }
; }
; __device__ __forceinline__ int v_st(int k, int c) { const int kk = (k & ~0xC) | ((k & 4) << 1) | ((k & 8) >> 1); return ((kk >> 3) * 4 + (c >> 5)) * 512 + ((kk & 7) * 32 + (c & 31)) * 2; }
; __device__ __forceinline__ int v_rd_base(int lane) { return ((lane & 3) << 3) | (((lane >> 2) & 3) << 6) | (((lane >> 4) & 1) << 5) | (((lane >> 5) & 1) << 8); }
; template <int OFF> __device__ __forceinline__ s16x4 tr_read(int vb) {
;   s16x4 r; asm volatile("ds_read_b64_tr_b16 %0, %1 offset:%2" : "=&v"(r) : "v"(vb), "i"(OFF) : "memory"); return r;
; }
; template <int D0> __device__ __forceinline__ void pv_one(f32x16& od, int vb, bf16x8 pa0, bf16x8 pa1, bf16x8 pa2, bf16x8 pa3) {
;   const s16x4 l0 = tr_read<v_rd_off(D0, 0, 0)>(vb), h0 = tr_read<v_rd_off(D0, 0, 1)>(vb), l1 = tr_read<v_rd_off(D0, 1, 0)>(vb), h1 = tr_read<v_rd_off(D0, 1, 1)>(vb);
;   const s16x4 l2 = tr_read<v_rd_off(D0, 2, 0)>(vb), h2 = tr_read<v_rd_off(D0, 2, 1)>(vb), l3 = tr_read<v_rd_off(D0, 3, 0)>(vb), h3 = tr_read<v_rd_off(D0, 3, 1)>(vb);
;   asm volatile("s_waitcnt lgkmcnt(0)" ::: "memory"); SBAR();
;     ...
;   od = __builtin_amdgcn_mfma_f32_32x32x16_bf16(pa0, PK(l0, h0), od, 0, 0, 0);
	s_waitcnt lgkmcnt(7)
	v_mfma_f32_16x16x32_bf16 v[64:67], v[200:203], v[96:99], 0
	v_add_f32_e32 v169, v169, v128
	s_add_i32 m0, s32, 0x4000
	s_nop 0
	global_load_lds_dwordx4 v183, s[98:99]
	v_mfma_f32_16x16x32_bf16 v[68:71], v[200:203], v[112:115], 0
	ds_read_b128 v[200:203], v174 offset:32768
	v_add_f32_e32 v169, v169, v129
	v_cvt_pk_bf16_f32 v184, v128, v129
	s_waitcnt lgkmcnt(7)
	v_mfma_f32_16x16x32_bf16 v[72:75], v[204:207], v[96:99], 0
	v_add_f32_e32 v169, v169, v130
	v_mfma_f32_16x16x32_bf16 v[76:79], v[204:207], v[112:115], 0
	ds_read_b128 v[204:207], v174 offset:36864
	v_add_f32_e32 v169, v169, v131
	v_cvt_pk_bf16_f32 v185, v130, v131
	s_waitcnt lgkmcnt(7)
	v_mfma_f32_16x16x32_bf16 v[80:83], v[208:211], v[96:99], 0
	v_add_f32_e32 v222, v222, v132
	s_add_i32 m0, s32, 0x6000
	s_nop 0
	global_load_lds_dwordx4 v183, s[100:101]
	s_add_u32 s98, s98, 0x150000
	s_addc_u32 s99, s99, 0
	s_add_u32 s100, s100, 0x150000
	s_addc_u32 s101, s101, 0
	v_mfma_f32_16x16x32_bf16 v[84:87], v[208:211], v[112:115], 0
	ds_read_b128 v[208:211], v174 offset:40960
	v_add_f32_e32 v222, v222, v133
	v_cvt_pk_bf16_f32 v186, v136, v137
	s_waitcnt lgkmcnt(7)
	v_mfma_f32_16x16x32_bf16 v[88:91], v[212:215], v[96:99], 0
	v_add_f32_e32 v222, v222, v134
	v_mfma_f32_16x16x32_bf16 v[92:95], v[212:215], v[112:115], 0
	ds_read_b128 v[212:215], v174 offset:45056
	v_add_f32_e32 v222, v222, v135
	v_cvt_pk_bf16_f32 v187, v138, v139
	s_waitcnt lgkmcnt(7)
	v_mfma_f32_16x16x32_bf16 v[64:67], v[230:233], v[100:103], v[64:67]
	v_add_f32_e32 v169, v169, v136
	s_add_i32 m0, s32, 0x1c000
	s_nop 0
	global_load_lds_dwordx4 v181, s[0:1]
	v_mfma_f32_16x16x32_bf16 v[68:71], v[230:233], v[116:119], v[68:71]
	ds_read_b128 v[230:233], v175 offset:32768
	v_add_f32_e32 v169, v169, v137
	v_cvt_pk_bf16_f32 v188, v144, v145
	s_waitcnt lgkmcnt(7)
	v_mfma_f32_16x16x32_bf16 v[72:75], v[234:237], v[100:103], v[72:75]
	v_add_f32_e32 v169, v169, v138
	v_mfma_f32_16x16x32_bf16 v[76:79], v[234:237], v[116:119], v[76:79]
	ds_read_b128 v[234:237], v175 offset:36864
	v_add_f32_e32 v169, v169, v139
	v_cvt_pk_bf16_f32 v189, v146, v147
	s_waitcnt lgkmcnt(7)
	v_mfma_f32_16x16x32_bf16 v[80:83], v[238:241], v[100:103], v[80:83]
	v_add_f32_e32 v222, v222, v140
	s_add_i32 m0, s32, 0x1e000
	s_nop 0
	global_load_lds_dwordx4 v181, s[4:5]
	s_add_u32 s0, s0, 0x150000
	s_addc_u32 s1, s1, 0
	s_add_u32 s4, s4, 0x150000
	s_addc_u32 s5, s5, 0
	v_mfma_f32_16x16x32_bf16 v[84:87], v[238:241], v[116:119], v[84:87]
	ds_read_b128 v[238:241], v175 offset:40960
	v_add_f32_e32 v222, v222, v141
	v_cvt_pk_bf16_f32 v190, v152, v153
	s_waitcnt lgkmcnt(7)
	v_mfma_f32_16x16x32_bf16 v[88:91], v[242:245], v[100:103], v[88:91]
	v_add_f32_e32 v222, v222, v142
	v_mfma_f32_16x16x32_bf16 v[92:95], v[242:245], v[116:119], v[92:95]
	ds_read_b128 v[242:245], v175 offset:45056
	v_add_f32_e32 v222, v222, v143
	v_cvt_pk_bf16_f32 v191, v154, v155
	s_waitcnt lgkmcnt(7)
	v_mfma_f32_16x16x32_bf16 v[64:67], v[200:203], v[104:107], v[64:67]
	v_add_f32_e32 v169, v169, v144
	v_mfma_f32_16x16x32_bf16 v[68:71], v[200:203], v[120:123], v[68:71]
	v_add_f32_e32 v169, v169, v145
	v_cvt_pk_bf16_f32 v192, v132, v133
	s_waitcnt lgkmcnt(6)
	v_mfma_f32_16x16x32_bf16 v[72:75], v[204:207], v[104:107], v[72:75]
	ds_read_b64_tr_b16 v[200:201], v176 offset:16384
	ds_read_b64_tr_b16 v[202:203], v176 offset:20480
	v_add_f32_e32 v169, v169, v146
	v_mfma_f32_16x16x32_bf16 v[76:79], v[204:207], v[120:123], v[76:79]
	v_add_f32_e32 v169, v169, v147
	v_cvt_pk_bf16_f32 v193, v134, v135
	s_waitcnt lgkmcnt(7)
	v_mfma_f32_16x16x32_bf16 v[80:83], v[208:211], v[104:107], v[80:83]
	ds_read_b64_tr_b16 v[204:205], v177 offset:16384
	ds_read_b64_tr_b16 v[206:207], v177 offset:20480
	v_add_f32_e32 v222, v222, v148
	v_mfma_f32_16x16x32_bf16 v[84:87], v[208:211], v[120:123], v[84:87]
	v_add_f32_e32 v222, v222, v149
	v_cvt_pk_bf16_f32 v194, v140, v141
	s_waitcnt lgkmcnt(8)
	v_mfma_f32_16x16x32_bf16 v[88:91], v[212:215], v[104:107], v[88:91]
	ds_read_b64_tr_b16 v[208:209], v178 offset:16384
	ds_read_b64_tr_b16 v[210:211], v178 offset:20480
	v_add_f32_e32 v222, v222, v150
	v_mfma_f32_16x16x32_bf16 v[92:95], v[212:215], v[120:123], v[92:95]
	v_add_f32_e32 v222, v222, v151
	v_cvt_pk_bf16_f32 v195, v142, v143
	s_waitcnt lgkmcnt(9)
	v_mfma_f32_16x16x32_bf16 v[64:67], v[230:233], v[108:111], v[64:67]
	ds_read_b64_tr_b16 v[212:213], v179 offset:16384
	ds_read_b64_tr_b16 v[214:215], v179 offset:20480
	v_add_f32_e32 v169, v169, v152
	v_mfma_f32_16x16x32_bf16 v[68:71], v[230:233], v[124:127], v[68:71]
	v_add_f32_e32 v169, v169, v153
	v_cvt_pk_bf16_f32 v196, v148, v149
	s_waitcnt lgkmcnt(10)
	v_mfma_f32_16x16x32_bf16 v[72:75], v[234:237], v[108:111], v[72:75]
	ds_read_b64_tr_b16 v[230:231], v180 offset:16384
	ds_read_b64_tr_b16 v[232:233], v180 offset:20480
	v_add_f32_e32 v169, v169, v154
	v_mfma_f32_16x16x32_bf16 v[76:79], v[234:237], v[124:127], v[76:79]
	v_add_f32_e32 v169, v169, v155
	v_cvt_pk_bf16_f32 v197, v150, v151
	s_waitcnt lgkmcnt(11)
	v_mfma_f32_16x16x32_bf16 v[80:83], v[238:241], v[108:111], v[80:83]
	ds_read_b64_tr_b16 v[234:235], v182 offset:16384
	ds_read_b64_tr_b16 v[236:237], v182 offset:20480
	v_add_f32_e32 v222, v222, v156
	v_mfma_f32_16x16x32_bf16 v[84:87], v[238:241], v[124:127], v[84:87]
	v_add_f32_e32 v222, v222, v157
	v_cvt_pk_bf16_f32 v198, v156, v157
	s_waitcnt lgkmcnt(12)
	v_mfma_f32_16x16x32_bf16 v[88:91], v[242:245], v[108:111], v[88:91]
	ds_read_b64_tr_b16 v[238:239], v216 offset:16384
	ds_read_b64_tr_b16 v[240:241], v216 offset:20480
	v_add_f32_e32 v222, v222, v158
	v_mfma_f32_16x16x32_bf16 v[92:95], v[242:245], v[124:127], v[92:95]
	v_add_f32_e32 v222, v222, v159
	v_cvt_pk_bf16_f32 v199, v158, v159
	s_waitcnt lgkmcnt(12)
; __device__ __forceinline__ void finishSM(f32x16& p0, f32x16& p1, float alpha, float& l_reg, bf16x8& pa0, bf16x8& pa1, bf16x8& pa2, bf16x8& pa3) {
; #pragma unroll
;   for (int r = 0; r < 16; ++r) p1[r] = __builtin_amdgcn_exp2f(p1[r]);
;   float ps = 0;
; #pragma unroll
;   for (int r = 0; r < 16; ++r) ps += p0[r];
; #pragma unroll
;   for (int r = 0; r < 16; ++r) ps += p1[r];
;   { auto rr = __builtin_amdgcn_permlane32_swap(__float_as_uint(ps), __float_as_uint(ps), false, false);
;     ps = __uint_as_float(rr[0]) + __uint_as_float(rr[1]); }
;   l_reg = l_reg * alpha + ps;
;     ...
;   PK4(p0, 0, pa0); PK4(p0, 8, pa1); PK4(p1, 0, pa2); PK4(p1, 8, pa3);
;     ...
; }
; __device__ __forceinline__ void qkt(f32x16& p0, f32x16& p1, const bf16* Ks, const bf16x8* qr, int r32, int hi) {
;   p0 = f32x16{}; p1 = f32x16{};
; #pragma unroll
;   for (int d0 = 0; d0 < 8; ++d0) { int cb = (d0 * 16 + hi * 8) * 2;
;     bf16x8 b0 = *reinterpret_cast<const bf16x8*>((const char*)Ks + KSWZ(r32, cb));
;     bf16x8 b1 = *reinterpret_cast<const bf16x8*>((const char*)Ks + KSWZ(32 + r32, cb));
;     p0 = __builtin_amdgcn_mfma_f32_32x32x16_bf16(b0, qr[d0], p0, 0, 0, 0);
;     p1 = __builtin_amdgcn_mfma_f32_32x32x16_bf16(b1, qr[d0], p1, 0, 0, 0); }
; }
; __device__ __forceinline__ int v_st(int k, int c) { const int kk = (k & ~0xC) | ((k & 4) << 1) | ((k & 8) >> 1); return ((kk >> 3) * 4 + (c >> 5)) * 512 + ((kk & 7) * 32 + (c & 31)) * 2; }
; __device__ __forceinline__ int v_rd_base(int lane) { return ((lane & 3) << 3) | (((lane >> 2) & 3) << 6) | (((lane >> 4) & 1) << 5) | (((lane >> 5) & 1) << 8); }
; template <int OFF> __device__ __forceinline__ s16x4 tr_read(int vb) {
;   s16x4 r; asm volatile("ds_read_b64_tr_b16 %0, %1 offset:%2" : "=&v"(r) : "v"(vb), "i"(OFF) : "memory"); return r;
; }
; template <int D0> __device__ __forceinline__ void pv_one(f32x16& od, int vb, bf16x8 pa0, bf16x8 pa1, bf16x8 pa2, bf16x8 pa3) {
;   const s16x4 l0 = tr_read<v_rd_off(D0, 0, 0)>(vb), h0 = tr_read<v_rd_off(D0, 0, 1)>(vb), l1 = tr_read<v_rd_off(D0, 1, 0)>(vb), h1 = tr_read<v_rd_off(D0, 1, 1)>(vb);
;   const s16x4 l2 = tr_read<v_rd_off(D0, 2, 0)>(vb), h2 = tr_read<v_rd_off(D0, 2, 1)>(vb), l3 = tr_read<v_rd_off(D0, 3, 0)>(vb), h3 = tr_read<v_rd_off(D0, 3, 1)>(vb);
;   asm volatile("s_waitcnt lgkmcnt(0)" ::: "memory"); SBAR();
;     ...
;   od = __builtin_amdgcn_mfma_f32_32x32x16_bf16(pa0, PK(l0, h0), od, 0, 0, 0);
	v_mfma_f32_16x16x32_bf16 v[0:3], v[200:203], v[184:187], v[0:3]
	v_exp_f32_e32 v64, v64
	v_mfma_f32_16x16x32_bf16 v[32:35], v[200:203], v[192:195], v[32:35]
	ds_read_b64_tr_b16 v[242:243], v217 offset:16384
	ds_read_b64_tr_b16 v[244:245], v217 offset:20480
	v_exp_f32_e32 v65, v65
	s_waitcnt lgkmcnt(12)
	v_mfma_f32_16x16x32_bf16 v[4:7], v[204:207], v[184:187], v[4:7]
	v_exp_f32_e32 v66, v66
	v_mfma_f32_16x16x32_bf16 v[36:39], v[204:207], v[192:195], v[36:39]
	ds_read_b64_tr_b16 v[200:201], v176 offset:24576
	ds_read_b64_tr_b16 v[202:203], v176 offset:28672
	v_exp_f32_e32 v67, v67
	s_waitcnt lgkmcnt(12)
	v_mfma_f32_16x16x32_bf16 v[8:11], v[208:211], v[184:187], v[8:11]
	v_exp_f32_e32 v68, v68
	v_mfma_f32_16x16x32_bf16 v[40:43], v[208:211], v[192:195], v[40:43]
	ds_read_b64_tr_b16 v[204:205], v177 offset:24576
	ds_read_b64_tr_b16 v[206:207], v177 offset:28672
	v_exp_f32_e32 v69, v69
	s_waitcnt lgkmcnt(12)
	v_mfma_f32_16x16x32_bf16 v[12:15], v[212:215], v[184:187], v[12:15]
	v_exp_f32_e32 v70, v70
	v_mfma_f32_16x16x32_bf16 v[44:47], v[212:215], v[192:195], v[44:47]
	ds_read_b64_tr_b16 v[208:209], v178 offset:24576
	ds_read_b64_tr_b16 v[210:211], v178 offset:28672
	v_exp_f32_e32 v71, v71
	s_waitcnt lgkmcnt(12)
	v_mfma_f32_16x16x32_bf16 v[16:19], v[230:233], v[184:187], v[16:19]
	v_exp_f32_e32 v72, v72
	v_mfma_f32_16x16x32_bf16 v[48:51], v[230:233], v[192:195], v[48:51]
	ds_read_b64_tr_b16 v[212:213], v179 offset:24576
	ds_read_b64_tr_b16 v[214:215], v179 offset:28672
	v_exp_f32_e32 v73, v73
	s_waitcnt lgkmcnt(12)
	v_mfma_f32_16x16x32_bf16 v[20:23], v[234:237], v[184:187], v[20:23]
	v_exp_f32_e32 v74, v74
	v_mfma_f32_16x16x32_bf16 v[52:55], v[234:237], v[192:195], v[52:55]
	ds_read_b64_tr_b16 v[230:231], v180 offset:24576
	ds_read_b64_tr_b16 v[232:233], v180 offset:28672
	v_exp_f32_e32 v75, v75
	s_waitcnt lgkmcnt(12)
	v_mfma_f32_16x16x32_bf16 v[24:27], v[238:241], v[184:187], v[24:27]
	v_exp_f32_e32 v76, v76
	v_mfma_f32_16x16x32_bf16 v[56:59], v[238:241], v[192:195], v[56:59]
	ds_read_b64_tr_b16 v[234:235], v182 offset:24576
	ds_read_b64_tr_b16 v[236:237], v182 offset:28672
	v_exp_f32_e32 v77, v77
	s_waitcnt lgkmcnt(12)
	v_mfma_f32_16x16x32_bf16 v[28:31], v[242:245], v[184:187], v[28:31]
	v_exp_f32_e32 v78, v78
	v_mfma_f32_16x16x32_bf16 v[60:63], v[242:245], v[192:195], v[60:63]
	ds_read_b64_tr_b16 v[238:239], v216 offset:24576
	ds_read_b64_tr_b16 v[240:241], v216 offset:28672
	v_exp_f32_e32 v79, v79
	s_waitcnt lgkmcnt(12)
	v_mfma_f32_16x16x32_bf16 v[0:3], v[200:203], v[188:191], v[0:3]
	v_exp_f32_e32 v80, v80
	v_mfma_f32_16x16x32_bf16 v[32:35], v[200:203], v[196:199], v[32:35]
	ds_read_b64_tr_b16 v[242:243], v217 offset:24576
	ds_read_b64_tr_b16 v[244:245], v217 offset:28672
	ds_read_b128 v[200:203], v172 offset:49152
	v_exp_f32_e32 v81, v81
	s_waitcnt lgkmcnt(13)
	v_mfma_f32_16x16x32_bf16 v[4:7], v[204:207], v[188:191], v[4:7]
	v_exp_f32_e32 v82, v82
	v_mfma_f32_16x16x32_bf16 v[36:39], v[204:207], v[196:199], v[36:39]
	ds_read_b128 v[204:207], v172 offset:53248
	v_exp_f32_e32 v83, v83
	s_waitcnt lgkmcnt(12)
	v_mfma_f32_16x16x32_bf16 v[8:11], v[208:211], v[188:191], v[8:11]
	v_exp_f32_e32 v84, v84
	v_mfma_f32_16x16x32_bf16 v[40:43], v[208:211], v[196:199], v[40:43]
	ds_read_b128 v[208:211], v172 offset:57344
	v_exp_f32_e32 v85, v85
	s_waitcnt lgkmcnt(11)
	v_mfma_f32_16x16x32_bf16 v[12:15], v[212:215], v[188:191], v[12:15]
	v_exp_f32_e32 v86, v86
	v_mfma_f32_16x16x32_bf16 v[44:47], v[212:215], v[196:199], v[44:47]
	ds_read_b128 v[212:215], v172 offset:61440
	v_exp_f32_e32 v87, v87
	s_waitcnt lgkmcnt(10)
	v_mfma_f32_16x16x32_bf16 v[16:19], v[230:233], v[188:191], v[16:19]
	v_exp_f32_e32 v88, v88
	v_mfma_f32_16x16x32_bf16 v[48:51], v[230:233], v[196:199], v[48:51]
	ds_read_b128 v[230:233], v173 offset:49152
	v_exp_f32_e32 v89, v89
	s_waitcnt lgkmcnt(9)
	v_mfma_f32_16x16x32_bf16 v[20:23], v[234:237], v[188:191], v[20:23]
	v_exp_f32_e32 v90, v90
	v_mfma_f32_16x16x32_bf16 v[52:55], v[234:237], v[196:199], v[52:55]
	ds_read_b128 v[234:237], v173 offset:53248
	v_exp_f32_e32 v91, v91
	s_waitcnt lgkmcnt(8)
	v_mfma_f32_16x16x32_bf16 v[24:27], v[238:241], v[188:191], v[24:27]
	v_exp_f32_e32 v92, v92
	v_mfma_f32_16x16x32_bf16 v[56:59], v[238:241], v[196:199], v[56:59]
	ds_read_b128 v[238:241], v173 offset:57344
	v_exp_f32_e32 v93, v93
	s_waitcnt lgkmcnt(7)
	v_mfma_f32_16x16x32_bf16 v[28:31], v[242:245], v[188:191], v[28:31]
	v_exp_f32_e32 v94, v94
	v_mfma_f32_16x16x32_bf16 v[60:63], v[242:245], v[196:199], v[60:63]
	ds_read_b128 v[242:245], v173 offset:61440
	v_exp_f32_e32 v95, v95
	s_waitcnt vmcnt(4)
	s_barrier
; __device__ __forceinline__ void finishSM(f32x16& p0, f32x16& p1, float alpha, float& l_reg, bf16x8& pa0, bf16x8& pa1, bf16x8& pa2, bf16x8& pa3) {
; #pragma unroll
;   for (int r = 0; r < 16; ++r) p1[r] = __builtin_amdgcn_exp2f(p1[r]);
;   float ps = 0;
; #pragma unroll
;   for (int r = 0; r < 16; ++r) ps += p0[r];
; #pragma unroll
;   for (int r = 0; r < 16; ++r) ps += p1[r];
;   { auto rr = __builtin_amdgcn_permlane32_swap(__float_as_uint(ps), __float_as_uint(ps), false, false);
;     ps = __uint_as_float(rr[0]) + __uint_as_float(rr[1]); }
;   l_reg = l_reg * alpha + ps;
;     ...
;   PK4(p0, 0, pa0); PK4(p0, 8, pa1); PK4(p1, 0, pa2); PK4(p1, 8, pa3);
;     ...
; }
; __device__ __forceinline__ void qkt(f32x16& p0, f32x16& p1, const bf16* Ks, const bf16x8* qr, int r32, int hi) {
;   p0 = f32x16{}; p1 = f32x16{};
; #pragma unroll
;   for (int d0 = 0; d0 < 8; ++d0) { int cb = (d0 * 16 + hi * 8) * 2;
;     bf16x8 b0 = *reinterpret_cast<const bf16x8*>((const char*)Ks + KSWZ(r32, cb));
;     bf16x8 b1 = *reinterpret_cast<const bf16x8*>((const char*)Ks + KSWZ(32 + r32, cb));
;     p0 = __builtin_amdgcn_mfma_f32_32x32x16_bf16(b0, qr[d0], p0, 0, 0, 0);
;     p1 = __builtin_amdgcn_mfma_f32_32x32x16_bf16(b1, qr[d0], p1, 0, 0, 0); }
; }
; __device__ __forceinline__ int v_st(int k, int c) { const int kk = (k & ~0xC) | ((k & 4) << 1) | ((k & 8) >> 1); return ((kk >> 3) * 4 + (c >> 5)) * 512 + ((kk & 7) * 32 + (c & 31)) * 2; }
; __device__ __forceinline__ int v_rd_base(int lane) { return ((lane & 3) << 3) | (((lane >> 2) & 3) << 6) | (((lane >> 4) & 1) << 5) | (((lane >> 5) & 1) << 8); }
; template <int OFF> __device__ __forceinline__ s16x4 tr_read(int vb) {
;   s16x4 r; asm volatile("ds_read_b64_tr_b16 %0, %1 offset:%2" : "=&v"(r) : "v"(vb), "i"(OFF) : "memory"); return r;
; }
; template <int D0> __device__ __forceinline__ void pv_one(f32x16& od, int vb, bf16x8 pa0, bf16x8 pa1, bf16x8 pa2, bf16x8 pa3) {
;   const s16x4 l0 = tr_read<v_rd_off(D0, 0, 0)>(vb), h0 = tr_read<v_rd_off(D0, 0, 1)>(vb), l1 = tr_read<v_rd_off(D0, 1, 0)>(vb), h1 = tr_read<v_rd_off(D0, 1, 1)>(vb);
;   const s16x4 l2 = tr_read<v_rd_off(D0, 2, 0)>(vb), h2 = tr_read<v_rd_off(D0, 2, 1)>(vb), l3 = tr_read<v_rd_off(D0, 3, 0)>(vb), h3 = tr_read<v_rd_off(D0, 3, 1)>(vb);
;   asm volatile("s_waitcnt lgkmcnt(0)" ::: "memory"); SBAR();
;     ...
;   od = __builtin_amdgcn_mfma_f32_32x32x16_bf16(pa0, PK(l0, h0), od, 0, 0, 0);
	s_waitcnt lgkmcnt(7)
	v_mfma_f32_16x16x32_bf16 v[128:131], v[200:203], v[96:99], 0
	v_add_f32_e32 v169, v169, v64
	s_add_i32 m0, s32, 0x8000
	s_nop 0
	global_load_lds_dwordx4 v183, s[98:99]
	v_mfma_f32_16x16x32_bf16 v[132:135], v[200:203], v[112:115], 0
	ds_read_b128 v[200:203], v174 offset:49152
	v_add_f32_e32 v169, v169, v65
	v_cvt_pk_bf16_f32 v184, v64, v65
	s_waitcnt lgkmcnt(7)
	v_mfma_f32_16x16x32_bf16 v[136:139], v[204:207], v[96:99], 0
	v_add_f32_e32 v169, v169, v66
	v_mfma_f32_16x16x32_bf16 v[140:143], v[204:207], v[112:115], 0
	ds_read_b128 v[204:207], v174 offset:53248
	v_add_f32_e32 v169, v169, v67
	v_cvt_pk_bf16_f32 v185, v66, v67
	s_waitcnt lgkmcnt(7)
	v_mfma_f32_16x16x32_bf16 v[144:147], v[208:211], v[96:99], 0
	v_add_f32_e32 v222, v222, v68
	s_add_i32 m0, s32, 0xa000
	s_nop 0
	global_load_lds_dwordx4 v183, s[100:101]
	s_add_u32 s98, s98, 0x150000
	s_addc_u32 s99, s99, 0
	s_add_u32 s100, s100, 0x150000
	s_addc_u32 s101, s101, 0
	v_mfma_f32_16x16x32_bf16 v[148:151], v[208:211], v[112:115], 0
	ds_read_b128 v[208:211], v174 offset:57344
	v_add_f32_e32 v222, v222, v69
	v_cvt_pk_bf16_f32 v186, v72, v73
	s_waitcnt lgkmcnt(7)
	v_mfma_f32_16x16x32_bf16 v[152:155], v[212:215], v[96:99], 0
	v_add_f32_e32 v222, v222, v70
	v_mfma_f32_16x16x32_bf16 v[156:159], v[212:215], v[112:115], 0
	ds_read_b128 v[212:215], v174 offset:61440
	v_add_f32_e32 v222, v222, v71
	v_cvt_pk_bf16_f32 v187, v74, v75
	s_waitcnt lgkmcnt(7)
	v_mfma_f32_16x16x32_bf16 v[128:131], v[230:233], v[100:103], v[128:131]
	v_add_f32_e32 v169, v169, v72
	s_add_i32 m0, s32, 0x10000
	s_nop 0
	global_load_lds_dwordx4 v181, s[0:1]
	v_mfma_f32_16x16x32_bf16 v[132:135], v[230:233], v[116:119], v[132:135]
	ds_read_b128 v[230:233], v175 offset:49152
	v_add_f32_e32 v169, v169, v73
	v_cvt_pk_bf16_f32 v188, v80, v81
	s_waitcnt lgkmcnt(7)
	v_mfma_f32_16x16x32_bf16 v[136:139], v[234:237], v[100:103], v[136:139]
	v_add_f32_e32 v169, v169, v74
	v_mfma_f32_16x16x32_bf16 v[140:143], v[234:237], v[116:119], v[140:143]
	ds_read_b128 v[234:237], v175 offset:53248
	v_add_f32_e32 v169, v169, v75
	v_cvt_pk_bf16_f32 v189, v82, v83
	s_waitcnt lgkmcnt(7)
	v_mfma_f32_16x16x32_bf16 v[144:147], v[238:241], v[100:103], v[144:147]
	v_add_f32_e32 v222, v222, v76
	s_add_i32 m0, s32, 0x12000
	s_nop 0
	global_load_lds_dwordx4 v181, s[4:5]
	s_add_u32 s0, s0, 0x150000
	s_addc_u32 s1, s1, 0
	s_add_u32 s4, s4, 0x150000
	s_addc_u32 s5, s5, 0
	v_mfma_f32_16x16x32_bf16 v[148:151], v[238:241], v[116:119], v[148:151]
	ds_read_b128 v[238:241], v175 offset:57344
	v_add_f32_e32 v222, v222, v77
	v_cvt_pk_bf16_f32 v190, v88, v89
	s_waitcnt lgkmcnt(7)
	v_mfma_f32_16x16x32_bf16 v[152:155], v[242:245], v[100:103], v[152:155]
	v_add_f32_e32 v222, v222, v78
	v_mfma_f32_16x16x32_bf16 v[156:159], v[242:245], v[116:119], v[156:159]
	ds_read_b128 v[242:245], v175 offset:61440
	v_add_f32_e32 v222, v222, v79
	v_cvt_pk_bf16_f32 v191, v90, v91
	s_waitcnt lgkmcnt(7)
	v_mfma_f32_16x16x32_bf16 v[128:131], v[200:203], v[104:107], v[128:131]
	v_add_f32_e32 v169, v169, v80
	v_mfma_f32_16x16x32_bf16 v[132:135], v[200:203], v[120:123], v[132:135]
	v_add_f32_e32 v169, v169, v81
	v_cvt_pk_bf16_f32 v192, v68, v69
	s_waitcnt lgkmcnt(6)
	v_mfma_f32_16x16x32_bf16 v[136:139], v[204:207], v[104:107], v[136:139]
	ds_read_b64_tr_b16 v[200:201], v176 offset:32768
	ds_read_b64_tr_b16 v[202:203], v176 offset:36864
	v_add_f32_e32 v169, v169, v82
	v_mfma_f32_16x16x32_bf16 v[140:143], v[204:207], v[120:123], v[140:143]
	v_add_f32_e32 v169, v169, v83
	v_cvt_pk_bf16_f32 v193, v70, v71
	s_waitcnt lgkmcnt(7)
	v_mfma_f32_16x16x32_bf16 v[144:147], v[208:211], v[104:107], v[144:147]
	ds_read_b64_tr_b16 v[204:205], v177 offset:32768
	ds_read_b64_tr_b16 v[206:207], v177 offset:36864
	v_add_f32_e32 v222, v222, v84
	v_mfma_f32_16x16x32_bf16 v[148:151], v[208:211], v[120:123], v[148:151]
	v_add_f32_e32 v222, v222, v85
	v_cvt_pk_bf16_f32 v194, v76, v77
	s_waitcnt lgkmcnt(8)
	v_mfma_f32_16x16x32_bf16 v[152:155], v[212:215], v[104:107], v[152:155]
	ds_read_b64_tr_b16 v[208:209], v178 offset:32768
	ds_read_b64_tr_b16 v[210:211], v178 offset:36864
	v_add_f32_e32 v222, v222, v86
	v_mfma_f32_16x16x32_bf16 v[156:159], v[212:215], v[120:123], v[156:159]
	v_add_f32_e32 v222, v222, v87
	v_cvt_pk_bf16_f32 v195, v78, v79
	s_waitcnt lgkmcnt(9)
	v_mfma_f32_16x16x32_bf16 v[128:131], v[230:233], v[108:111], v[128:131]
	ds_read_b64_tr_b16 v[212:213], v179 offset:32768
	ds_read_b64_tr_b16 v[214:215], v179 offset:36864
	v_add_f32_e32 v169, v169, v88
	v_mfma_f32_16x16x32_bf16 v[132:135], v[230:233], v[124:127], v[132:135]
	v_add_f32_e32 v169, v169, v89
	v_cvt_pk_bf16_f32 v196, v84, v85
	s_waitcnt lgkmcnt(10)
	v_mfma_f32_16x16x32_bf16 v[136:139], v[234:237], v[108:111], v[136:139]
	ds_read_b64_tr_b16 v[230:231], v180 offset:32768
	ds_read_b64_tr_b16 v[232:233], v180 offset:36864
	v_add_f32_e32 v169, v169, v90
	v_mfma_f32_16x16x32_bf16 v[140:143], v[234:237], v[124:127], v[140:143]
	v_add_f32_e32 v169, v169, v91
	v_cvt_pk_bf16_f32 v197, v86, v87
	s_waitcnt lgkmcnt(11)
	v_mfma_f32_16x16x32_bf16 v[144:147], v[238:241], v[108:111], v[144:147]
	ds_read_b64_tr_b16 v[234:235], v182 offset:32768
	ds_read_b64_tr_b16 v[236:237], v182 offset:36864
	v_add_f32_e32 v222, v222, v92
	v_mfma_f32_16x16x32_bf16 v[148:151], v[238:241], v[124:127], v[148:151]
	v_add_f32_e32 v222, v222, v93
	v_cvt_pk_bf16_f32 v198, v92, v93
	s_waitcnt lgkmcnt(12)
	v_mfma_f32_16x16x32_bf16 v[152:155], v[242:245], v[108:111], v[152:155]
	ds_read_b64_tr_b16 v[238:239], v216 offset:32768
	ds_read_b64_tr_b16 v[240:241], v216 offset:36864
	v_add_f32_e32 v222, v222, v94
	v_mfma_f32_16x16x32_bf16 v[156:159], v[242:245], v[124:127], v[156:159]
	v_add_f32_e32 v222, v222, v95
	v_cvt_pk_bf16_f32 v199, v94, v95
	s_waitcnt lgkmcnt(12)
; __device__ __forceinline__ void finishSM(f32x16& p0, f32x16& p1, float alpha, float& l_reg, bf16x8& pa0, bf16x8& pa1, bf16x8& pa2, bf16x8& pa3) {
; #pragma unroll
;   for (int r = 0; r < 16; ++r) p1[r] = __builtin_amdgcn_exp2f(p1[r]);
;   float ps = 0;
; #pragma unroll
;   for (int r = 0; r < 16; ++r) ps += p0[r];
; #pragma unroll
;   for (int r = 0; r < 16; ++r) ps += p1[r];
;   { auto rr = __builtin_amdgcn_permlane32_swap(__float_as_uint(ps), __float_as_uint(ps), false, false);
;     ps = __uint_as_float(rr[0]) + __uint_as_float(rr[1]); }
;   l_reg = l_reg * alpha + ps;
;     ...
;   PK4(p0, 0, pa0); PK4(p0, 8, pa1); PK4(p1, 0, pa2); PK4(p1, 8, pa3);
;     ...
; }
; __device__ __forceinline__ void qkt(f32x16& p0, f32x16& p1, const bf16* Ks, const bf16x8* qr, int r32, int hi) {
;   p0 = f32x16{}; p1 = f32x16{};
; #pragma unroll
;   for (int d0 = 0; d0 < 8; ++d0) { int cb = (d0 * 16 + hi * 8) * 2;
;     bf16x8 b0 = *reinterpret_cast<const bf16x8*>((const char*)Ks + KSWZ(r32, cb));
;     bf16x8 b1 = *reinterpret_cast<const bf16x8*>((const char*)Ks + KSWZ(32 + r32, cb));
;     p0 = __builtin_amdgcn_mfma_f32_32x32x16_bf16(b0, qr[d0], p0, 0, 0, 0);
;     p1 = __builtin_amdgcn_mfma_f32_32x32x16_bf16(b1, qr[d0], p1, 0, 0, 0); }
; }
; __device__ __forceinline__ int v_st(int k, int c) { const int kk = (k & ~0xC) | ((k & 4) << 1) | ((k & 8) >> 1); return ((kk >> 3) * 4 + (c >> 5)) * 512 + ((kk & 7) * 32 + (c & 31)) * 2; }
; __device__ __forceinline__ int v_rd_base(int lane) { return ((lane & 3) << 3) | (((lane >> 2) & 3) << 6) | (((lane >> 4) & 1) << 5) | (((lane >> 5) & 1) << 8); }
; template <int OFF> __device__ __forceinline__ s16x4 tr_read(int vb) {
;   s16x4 r; asm volatile("ds_read_b64_tr_b16 %0, %1 offset:%2" : "=&v"(r) : "v"(vb), "i"(OFF) : "memory"); return r;
; }
; template <int D0> __device__ __forceinline__ void pv_one(f32x16& od, int vb, bf16x8 pa0, bf16x8 pa1, bf16x8 pa2, bf16x8 pa3) {
;   const s16x4 l0 = tr_read<v_rd_off(D0, 0, 0)>(vb), h0 = tr_read<v_rd_off(D0, 0, 1)>(vb), l1 = tr_read<v_rd_off(D0, 1, 0)>(vb), h1 = tr_read<v_rd_off(D0, 1, 1)>(vb);
;   const s16x4 l2 = tr_read<v_rd_off(D0, 2, 0)>(vb), h2 = tr_read<v_rd_off(D0, 2, 1)>(vb), l3 = tr_read<v_rd_off(D0, 3, 0)>(vb), h3 = tr_read<v_rd_off(D0, 3, 1)>(vb);
;   asm volatile("s_waitcnt lgkmcnt(0)" ::: "memory"); SBAR();
;     ...
;   od = __builtin_amdgcn_mfma_f32_32x32x16_bf16(pa0, PK(l0, h0), od, 0, 0, 0);
	v_mfma_f32_16x16x32_bf16 v[0:3], v[200:203], v[184:187], v[0:3]
	v_exp_f32_e32 v128, v128
	v_mfma_f32_16x16x32_bf16 v[32:35], v[200:203], v[192:195], v[32:35]
	ds_read_b64_tr_b16 v[242:243], v217 offset:32768
	ds_read_b64_tr_b16 v[244:245], v217 offset:36864
	v_exp_f32_e32 v129, v129
	s_waitcnt lgkmcnt(12)
	v_mfma_f32_16x16x32_bf16 v[4:7], v[204:207], v[184:187], v[4:7]
	v_exp_f32_e32 v130, v130
	v_mfma_f32_16x16x32_bf16 v[36:39], v[204:207], v[192:195], v[36:39]
	ds_read_b64_tr_b16 v[200:201], v176 offset:40960
	ds_read_b64_tr_b16 v[202:203], v176 offset:45056
	v_exp_f32_e32 v131, v131
	s_waitcnt lgkmcnt(12)
	v_mfma_f32_16x16x32_bf16 v[8:11], v[208:211], v[184:187], v[8:11]
	v_exp_f32_e32 v132, v132
	v_mfma_f32_16x16x32_bf16 v[40:43], v[208:211], v[192:195], v[40:43]
	ds_read_b64_tr_b16 v[204:205], v177 offset:40960
	ds_read_b64_tr_b16 v[206:207], v177 offset:45056
	v_exp_f32_e32 v133, v133
	s_waitcnt lgkmcnt(12)
	v_mfma_f32_16x16x32_bf16 v[12:15], v[212:215], v[184:187], v[12:15]
	v_exp_f32_e32 v134, v134
	v_mfma_f32_16x16x32_bf16 v[44:47], v[212:215], v[192:195], v[44:47]
	ds_read_b64_tr_b16 v[208:209], v178 offset:40960
	ds_read_b64_tr_b16 v[210:211], v178 offset:45056
	v_exp_f32_e32 v135, v135
	s_waitcnt lgkmcnt(12)
	v_mfma_f32_16x16x32_bf16 v[16:19], v[230:233], v[184:187], v[16:19]
	v_exp_f32_e32 v136, v136
	v_mfma_f32_16x16x32_bf16 v[48:51], v[230:233], v[192:195], v[48:51]
	ds_read_b64_tr_b16 v[212:213], v179 offset:40960
	ds_read_b64_tr_b16 v[214:215], v179 offset:45056
	v_exp_f32_e32 v137, v137
	s_waitcnt lgkmcnt(12)
	v_mfma_f32_16x16x32_bf16 v[20:23], v[234:237], v[184:187], v[20:23]
	v_exp_f32_e32 v138, v138
	v_mfma_f32_16x16x32_bf16 v[52:55], v[234:237], v[192:195], v[52:55]
	ds_read_b64_tr_b16 v[230:231], v180 offset:40960
	ds_read_b64_tr_b16 v[232:233], v180 offset:45056
	v_exp_f32_e32 v139, v139
	s_waitcnt lgkmcnt(12)
	v_mfma_f32_16x16x32_bf16 v[24:27], v[238:241], v[184:187], v[24:27]
	v_exp_f32_e32 v140, v140
	v_mfma_f32_16x16x32_bf16 v[56:59], v[238:241], v[192:195], v[56:59]
	ds_read_b64_tr_b16 v[234:235], v182 offset:40960
	ds_read_b64_tr_b16 v[236:237], v182 offset:45056
	v_exp_f32_e32 v141, v141
	s_waitcnt lgkmcnt(12)
	v_mfma_f32_16x16x32_bf16 v[28:31], v[242:245], v[184:187], v[28:31]
	v_exp_f32_e32 v142, v142
	v_mfma_f32_16x16x32_bf16 v[60:63], v[242:245], v[192:195], v[60:63]
	ds_read_b64_tr_b16 v[238:239], v216 offset:40960
	ds_read_b64_tr_b16 v[240:241], v216 offset:45056
	v_exp_f32_e32 v143, v143
	s_waitcnt lgkmcnt(12)
	v_mfma_f32_16x16x32_bf16 v[0:3], v[200:203], v[188:191], v[0:3]
	v_exp_f32_e32 v144, v144
	v_mfma_f32_16x16x32_bf16 v[32:35], v[200:203], v[196:199], v[32:35]
	ds_read_b64_tr_b16 v[242:243], v217 offset:40960
	ds_read_b64_tr_b16 v[244:245], v217 offset:45056
	ds_read_b128 v[200:203], v172 offset:0
	v_exp_f32_e32 v145, v145
	s_waitcnt lgkmcnt(13)
	v_mfma_f32_16x16x32_bf16 v[4:7], v[204:207], v[188:191], v[4:7]
	v_exp_f32_e32 v146, v146
	v_mfma_f32_16x16x32_bf16 v[36:39], v[204:207], v[196:199], v[36:39]
	ds_read_b128 v[204:207], v172 offset:4096
	v_exp_f32_e32 v147, v147
	s_waitcnt lgkmcnt(12)
	v_mfma_f32_16x16x32_bf16 v[8:11], v[208:211], v[188:191], v[8:11]
	v_exp_f32_e32 v148, v148
	v_mfma_f32_16x16x32_bf16 v[40:43], v[208:211], v[196:199], v[40:43]
	ds_read_b128 v[208:211], v172 offset:8192
	v_exp_f32_e32 v149, v149
	s_waitcnt lgkmcnt(11)
	v_mfma_f32_16x16x32_bf16 v[12:15], v[212:215], v[188:191], v[12:15]
	v_exp_f32_e32 v150, v150
	v_mfma_f32_16x16x32_bf16 v[44:47], v[212:215], v[196:199], v[44:47]
	ds_read_b128 v[212:215], v172 offset:12288
	v_exp_f32_e32 v151, v151
	s_waitcnt lgkmcnt(10)
	v_mfma_f32_16x16x32_bf16 v[16:19], v[230:233], v[188:191], v[16:19]
	v_exp_f32_e32 v152, v152
	v_mfma_f32_16x16x32_bf16 v[48:51], v[230:233], v[196:199], v[48:51]
	ds_read_b128 v[230:233], v173 offset:0
	v_exp_f32_e32 v153, v153
	s_waitcnt lgkmcnt(9)
	v_mfma_f32_16x16x32_bf16 v[20:23], v[234:237], v[188:191], v[20:23]
	v_exp_f32_e32 v154, v154
	v_mfma_f32_16x16x32_bf16 v[52:55], v[234:237], v[196:199], v[52:55]
	ds_read_b128 v[234:237], v173 offset:4096
	v_exp_f32_e32 v155, v155
	s_waitcnt lgkmcnt(8)
	v_mfma_f32_16x16x32_bf16 v[24:27], v[238:241], v[188:191], v[24:27]
	v_exp_f32_e32 v156, v156
	v_mfma_f32_16x16x32_bf16 v[56:59], v[238:241], v[196:199], v[56:59]
	ds_read_b128 v[238:241], v173 offset:8192
	v_exp_f32_e32 v157, v157
	s_waitcnt lgkmcnt(7)
	v_mfma_f32_16x16x32_bf16 v[28:31], v[242:245], v[188:191], v[28:31]
	v_exp_f32_e32 v158, v158
	v_mfma_f32_16x16x32_bf16 v[60:63], v[242:245], v[196:199], v[60:63]
	ds_read_b128 v[242:245], v173 offset:12288
	v_exp_f32_e32 v159, v159
	s_waitcnt vmcnt(4)
	s_barrier
; __device__ __forceinline__ void finishSM(f32x16& p0, f32x16& p1, float alpha, float& l_reg, bf16x8& pa0, bf16x8& pa1, bf16x8& pa2, bf16x8& pa3) {
; #pragma unroll
;   for (int r = 0; r < 16; ++r) p1[r] = __builtin_amdgcn_exp2f(p1[r]);
;   float ps = 0;
; #pragma unroll
;   for (int r = 0; r < 16; ++r) ps += p0[r];
; #pragma unroll
;   for (int r = 0; r < 16; ++r) ps += p1[r];
;   { auto rr = __builtin_amdgcn_permlane32_swap(__float_as_uint(ps), __float_as_uint(ps), false, false);
;     ps = __uint_as_float(rr[0]) + __uint_as_float(rr[1]); }
;   l_reg = l_reg * alpha + ps;
;     ...
;   PK4(p0, 0, pa0); PK4(p0, 8, pa1); PK4(p1, 0, pa2); PK4(p1, 8, pa3);
;     ...
; }
; __device__ __forceinline__ void qkt(f32x16& p0, f32x16& p1, const bf16* Ks, const bf16x8* qr, int r32, int hi) {
;   p0 = f32x16{}; p1 = f32x16{};
; #pragma unroll
;   for (int d0 = 0; d0 < 8; ++d0) { int cb = (d0 * 16 + hi * 8) * 2;
;     bf16x8 b0 = *reinterpret_cast<const bf16x8*>((const char*)Ks + KSWZ(r32, cb));
;     bf16x8 b1 = *reinterpret_cast<const bf16x8*>((const char*)Ks + KSWZ(32 + r32, cb));
;     p0 = __builtin_amdgcn_mfma_f32_32x32x16_bf16(b0, qr[d0], p0, 0, 0, 0);
;     p1 = __builtin_amdgcn_mfma_f32_32x32x16_bf16(b1, qr[d0], p1, 0, 0, 0); }
; }
; __device__ __forceinline__ int v_st(int k, int c) { const int kk = (k & ~0xC) | ((k & 4) << 1) | ((k & 8) >> 1); return ((kk >> 3) * 4 + (c >> 5)) * 512 + ((kk & 7) * 32 + (c & 31)) * 2; }
; __device__ __forceinline__ int v_rd_base(int lane) { return ((lane & 3) << 3) | (((lane >> 2) & 3) << 6) | (((lane >> 4) & 1) << 5) | (((lane >> 5) & 1) << 8); }
; template <int OFF> __device__ __forceinline__ s16x4 tr_read(int vb) {
;   s16x4 r; asm volatile("ds_read_b64_tr_b16 %0, %1 offset:%2" : "=&v"(r) : "v"(vb), "i"(OFF) : "memory"); return r;
; }
; template <int D0> __device__ __forceinline__ void pv_one(f32x16& od, int vb, bf16x8 pa0, bf16x8 pa1, bf16x8 pa2, bf16x8 pa3) {
;   const s16x4 l0 = tr_read<v_rd_off(D0, 0, 0)>(vb), h0 = tr_read<v_rd_off(D0, 0, 1)>(vb), l1 = tr_read<v_rd_off(D0, 1, 0)>(vb), h1 = tr_read<v_rd_off(D0, 1, 1)>(vb);
;   const s16x4 l2 = tr_read<v_rd_off(D0, 2, 0)>(vb), h2 = tr_read<v_rd_off(D0, 2, 1)>(vb), l3 = tr_read<v_rd_off(D0, 3, 0)>(vb), h3 = tr_read<v_rd_off(D0, 3, 1)>(vb);
;   asm volatile("s_waitcnt lgkmcnt(0)" ::: "memory"); SBAR();
;     ...
;   od = __builtin_amdgcn_mfma_f32_32x32x16_bf16(pa0, PK(l0, h0), od, 0, 0, 0);
	s_waitcnt lgkmcnt(7)
	v_mfma_f32_16x16x32_bf16 v[64:67], v[200:203], v[96:99], 0
	v_add_f32_e32 v169, v169, v128
	s_add_i32 m0, s32, 0xc000
	s_nop 0
	global_load_lds_dwordx4 v183, s[98:99]
	v_mfma_f32_16x16x32_bf16 v[68:71], v[200:203], v[112:115], 0
	ds_read_b128 v[200:203], v174 offset:0
	v_add_f32_e32 v169, v169, v129
	v_cvt_pk_bf16_f32 v184, v128, v129
	s_waitcnt lgkmcnt(7)
	v_mfma_f32_16x16x32_bf16 v[72:75], v[204:207], v[96:99], 0
	v_add_f32_e32 v169, v169, v130
	v_mfma_f32_16x16x32_bf16 v[76:79], v[204:207], v[112:115], 0
	ds_read_b128 v[204:207], v174 offset:4096
	v_add_f32_e32 v169, v169, v131
	v_cvt_pk_bf16_f32 v185, v130, v131
	s_waitcnt lgkmcnt(7)
	v_mfma_f32_16x16x32_bf16 v[80:83], v[208:211], v[96:99], 0
	v_add_f32_e32 v222, v222, v132
	s_add_i32 m0, s32, 0xe000
	s_nop 0
	global_load_lds_dwordx4 v183, s[100:101]
	s_add_u32 s98, s98, 0x150000
	s_addc_u32 s99, s99, 0
	s_add_u32 s100, s100, 0x150000
	s_addc_u32 s101, s101, 0
	v_mfma_f32_16x16x32_bf16 v[84:87], v[208:211], v[112:115], 0
	ds_read_b128 v[208:211], v174 offset:8192
	v_add_f32_e32 v222, v222, v133
	v_cvt_pk_bf16_f32 v186, v136, v137
	s_waitcnt lgkmcnt(7)
	v_mfma_f32_16x16x32_bf16 v[88:91], v[212:215], v[96:99], 0
	v_add_f32_e32 v222, v222, v134
	v_mfma_f32_16x16x32_bf16 v[92:95], v[212:215], v[112:115], 0
	ds_read_b128 v[212:215], v174 offset:12288
	v_add_f32_e32 v222, v222, v135
	v_cvt_pk_bf16_f32 v187, v138, v139
	s_waitcnt lgkmcnt(7)
	v_mfma_f32_16x16x32_bf16 v[64:67], v[230:233], v[100:103], v[64:67]
	v_add_f32_e32 v169, v169, v136
	s_add_i32 m0, s32, 0x14000
	s_nop 0
	global_load_lds_dwordx4 v181, s[0:1]
	v_mfma_f32_16x16x32_bf16 v[68:71], v[230:233], v[116:119], v[68:71]
	ds_read_b128 v[230:233], v175 offset:0
	v_add_f32_e32 v169, v169, v137
	v_cvt_pk_bf16_f32 v188, v144, v145
	s_waitcnt lgkmcnt(7)
	v_mfma_f32_16x16x32_bf16 v[72:75], v[234:237], v[100:103], v[72:75]
	v_add_f32_e32 v169, v169, v138
	v_mfma_f32_16x16x32_bf16 v[76:79], v[234:237], v[116:119], v[76:79]
	ds_read_b128 v[234:237], v175 offset:4096
	v_add_f32_e32 v169, v169, v139
	v_cvt_pk_bf16_f32 v189, v146, v147
	s_waitcnt lgkmcnt(7)
	v_mfma_f32_16x16x32_bf16 v[80:83], v[238:241], v[100:103], v[80:83]
	v_add_f32_e32 v222, v222, v140
	s_add_i32 m0, s32, 0x16000
	s_nop 0
	global_load_lds_dwordx4 v181, s[4:5]
	s_add_u32 s0, s0, 0x150000
	s_addc_u32 s1, s1, 0
	s_add_u32 s4, s4, 0x150000
	s_addc_u32 s5, s5, 0
	v_mfma_f32_16x16x32_bf16 v[84:87], v[238:241], v[116:119], v[84:87]
	ds_read_b128 v[238:241], v175 offset:8192
	v_add_f32_e32 v222, v222, v141
	v_cvt_pk_bf16_f32 v190, v152, v153
	s_waitcnt lgkmcnt(7)
	v_mfma_f32_16x16x32_bf16 v[88:91], v[242:245], v[100:103], v[88:91]
	v_add_f32_e32 v222, v222, v142
	v_mfma_f32_16x16x32_bf16 v[92:95], v[242:245], v[116:119], v[92:95]
	ds_read_b128 v[242:245], v175 offset:12288
	v_add_f32_e32 v222, v222, v143
	v_cvt_pk_bf16_f32 v191, v154, v155
	s_waitcnt lgkmcnt(7)
	v_mfma_f32_16x16x32_bf16 v[64:67], v[200:203], v[104:107], v[64:67]
	v_add_f32_e32 v169, v169, v144
	v_mfma_f32_16x16x32_bf16 v[68:71], v[200:203], v[120:123], v[68:71]
	v_add_f32_e32 v169, v169, v145
	v_cvt_pk_bf16_f32 v192, v132, v133
	s_waitcnt lgkmcnt(6)
	v_mfma_f32_16x16x32_bf16 v[72:75], v[204:207], v[104:107], v[72:75]
	ds_read_b64_tr_b16 v[200:201], v176 offset:49152
	ds_read_b64_tr_b16 v[202:203], v176 offset:53248
	v_add_f32_e32 v169, v169, v146
	v_mfma_f32_16x16x32_bf16 v[76:79], v[204:207], v[120:123], v[76:79]
	v_add_f32_e32 v169, v169, v147
	v_cvt_pk_bf16_f32 v193, v134, v135
	s_waitcnt lgkmcnt(7)
	v_mfma_f32_16x16x32_bf16 v[80:83], v[208:211], v[104:107], v[80:83]
	ds_read_b64_tr_b16 v[204:205], v177 offset:49152
	ds_read_b64_tr_b16 v[206:207], v177 offset:53248
	v_add_f32_e32 v222, v222, v148
	v_mfma_f32_16x16x32_bf16 v[84:87], v[208:211], v[120:123], v[84:87]
	v_add_f32_e32 v222, v222, v149
	v_cvt_pk_bf16_f32 v194, v140, v141
	s_waitcnt lgkmcnt(8)
	v_mfma_f32_16x16x32_bf16 v[88:91], v[212:215], v[104:107], v[88:91]
	ds_read_b64_tr_b16 v[208:209], v178 offset:49152
	ds_read_b64_tr_b16 v[210:211], v178 offset:53248
	v_add_f32_e32 v222, v222, v150
	v_mfma_f32_16x16x32_bf16 v[92:95], v[212:215], v[120:123], v[92:95]
	v_add_f32_e32 v222, v222, v151
	v_cvt_pk_bf16_f32 v195, v142, v143
	s_waitcnt lgkmcnt(9)
	v_mfma_f32_16x16x32_bf16 v[64:67], v[230:233], v[108:111], v[64:67]
	ds_read_b64_tr_b16 v[212:213], v179 offset:49152
	ds_read_b64_tr_b16 v[214:215], v179 offset:53248
	v_add_f32_e32 v169, v169, v152
	v_mfma_f32_16x16x32_bf16 v[68:71], v[230:233], v[124:127], v[68:71]
	v_add_f32_e32 v169, v169, v153
	v_cvt_pk_bf16_f32 v196, v148, v149
	s_waitcnt lgkmcnt(10)
	v_mfma_f32_16x16x32_bf16 v[72:75], v[234:237], v[108:111], v[72:75]
	ds_read_b64_tr_b16 v[230:231], v180 offset:49152
	ds_read_b64_tr_b16 v[232:233], v180 offset:53248
	v_add_f32_e32 v169, v169, v154
	v_mfma_f32_16x16x32_bf16 v[76:79], v[234:237], v[124:127], v[76:79]
	v_add_f32_e32 v169, v169, v155
	v_cvt_pk_bf16_f32 v197, v150, v151
	s_waitcnt lgkmcnt(11)
	v_mfma_f32_16x16x32_bf16 v[80:83], v[238:241], v[108:111], v[80:83]
	ds_read_b64_tr_b16 v[234:235], v182 offset:49152
	ds_read_b64_tr_b16 v[236:237], v182 offset:53248
	v_add_f32_e32 v222, v222, v156
	v_mfma_f32_16x16x32_bf16 v[84:87], v[238:241], v[124:127], v[84:87]
	v_add_f32_e32 v222, v222, v157
	v_cvt_pk_bf16_f32 v198, v156, v157
	s_waitcnt lgkmcnt(12)
	v_mfma_f32_16x16x32_bf16 v[88:91], v[242:245], v[108:111], v[88:91]
	ds_read_b64_tr_b16 v[238:239], v216 offset:49152
	ds_read_b64_tr_b16 v[240:241], v216 offset:53248
	v_add_f32_e32 v222, v222, v158
	v_mfma_f32_16x16x32_bf16 v[92:95], v[242:245], v[124:127], v[92:95]
	v_add_f32_e32 v222, v222, v159
	v_cvt_pk_bf16_f32 v199, v158, v159
	s_waitcnt lgkmcnt(12)
; __device__ __forceinline__ void finishSM(f32x16& p0, f32x16& p1, float alpha, float& l_reg, bf16x8& pa0, bf16x8& pa1, bf16x8& pa2, bf16x8& pa3) {
; #pragma unroll
;   for (int r = 0; r < 16; ++r) p1[r] = __builtin_amdgcn_exp2f(p1[r]);
;   float ps = 0;
; #pragma unroll
;   for (int r = 0; r < 16; ++r) ps += p0[r];
; #pragma unroll
;   for (int r = 0; r < 16; ++r) ps += p1[r];
;   { auto rr = __builtin_amdgcn_permlane32_swap(__float_as_uint(ps), __float_as_uint(ps), false, false);
;     ps = __uint_as_float(rr[0]) + __uint_as_float(rr[1]); }
;   l_reg = l_reg * alpha + ps;
;     ...
;   PK4(p0, 0, pa0); PK4(p0, 8, pa1); PK4(p1, 0, pa2); PK4(p1, 8, pa3);
;     ...
; }
; __device__ __forceinline__ void qkt(f32x16& p0, f32x16& p1, const bf16* Ks, const bf16x8* qr, int r32, int hi) {
;   p0 = f32x16{}; p1 = f32x16{};
; #pragma unroll
;   for (int d0 = 0; d0 < 8; ++d0) { int cb = (d0 * 16 + hi * 8) * 2;
;     bf16x8 b0 = *reinterpret_cast<const bf16x8*>((const char*)Ks + KSWZ(r32, cb));
;     bf16x8 b1 = *reinterpret_cast<const bf16x8*>((const char*)Ks + KSWZ(32 + r32, cb));
;     p0 = __builtin_amdgcn_mfma_f32_32x32x16_bf16(b0, qr[d0], p0, 0, 0, 0);
;     p1 = __builtin_amdgcn_mfma_f32_32x32x16_bf16(b1, qr[d0], p1, 0, 0, 0); }
; }
; __device__ __forceinline__ int v_st(int k, int c) { const int kk = (k & ~0xC) | ((k & 4) << 1) | ((k & 8) >> 1); return ((kk >> 3) * 4 + (c >> 5)) * 512 + ((kk & 7) * 32 + (c & 31)) * 2; }
; __device__ __forceinline__ int v_rd_base(int lane) { return ((lane & 3) << 3) | (((lane >> 2) & 3) << 6) | (((lane >> 4) & 1) << 5) | (((lane >> 5) & 1) << 8); }
; template <int OFF> __device__ __forceinline__ s16x4 tr_read(int vb) {
;   s16x4 r; asm volatile("ds_read_b64_tr_b16 %0, %1 offset:%2" : "=&v"(r) : "v"(vb), "i"(OFF) : "memory"); return r;
; }
; template <int D0> __device__ __forceinline__ void pv_one(f32x16& od, int vb, bf16x8 pa0, bf16x8 pa1, bf16x8 pa2, bf16x8 pa3) {
;   const s16x4 l0 = tr_read<v_rd_off(D0, 0, 0)>(vb), h0 = tr_read<v_rd_off(D0, 0, 1)>(vb), l1 = tr_read<v_rd_off(D0, 1, 0)>(vb), h1 = tr_read<v_rd_off(D0, 1, 1)>(vb);
;   const s16x4 l2 = tr_read<v_rd_off(D0, 2, 0)>(vb), h2 = tr_read<v_rd_off(D0, 2, 1)>(vb), l3 = tr_read<v_rd_off(D0, 3, 0)>(vb), h3 = tr_read<v_rd_off(D0, 3, 1)>(vb);
;   asm volatile("s_waitcnt lgkmcnt(0)" ::: "memory"); SBAR();
;     ...
;   od = __builtin_amdgcn_mfma_f32_32x32x16_bf16(pa0, PK(l0, h0), od, 0, 0, 0);
	v_mfma_f32_16x16x32_bf16 v[0:3], v[200:203], v[184:187], v[0:3]
	v_exp_f32_e32 v64, v64
	v_mfma_f32_16x16x32_bf16 v[32:35], v[200:203], v[192:195], v[32:35]
	ds_read_b64_tr_b16 v[242:243], v217 offset:49152
	ds_read_b64_tr_b16 v[244:245], v217 offset:53248
	v_exp_f32_e32 v65, v65
	s_waitcnt lgkmcnt(12)
	v_mfma_f32_16x16x32_bf16 v[4:7], v[204:207], v[184:187], v[4:7]
	v_exp_f32_e32 v66, v66
	v_mfma_f32_16x16x32_bf16 v[36:39], v[204:207], v[192:195], v[36:39]
	ds_read_b64_tr_b16 v[200:201], v176 offset:57344
	ds_read_b64_tr_b16 v[202:203], v176 offset:61440
	v_exp_f32_e32 v67, v67
	s_waitcnt lgkmcnt(12)
	v_mfma_f32_16x16x32_bf16 v[8:11], v[208:211], v[184:187], v[8:11]
	v_exp_f32_e32 v68, v68
	v_mfma_f32_16x16x32_bf16 v[40:43], v[208:211], v[192:195], v[40:43]
	ds_read_b64_tr_b16 v[204:205], v177 offset:57344
	ds_read_b64_tr_b16 v[206:207], v177 offset:61440
	v_exp_f32_e32 v69, v69
	s_waitcnt lgkmcnt(12)
	v_mfma_f32_16x16x32_bf16 v[12:15], v[212:215], v[184:187], v[12:15]
	v_exp_f32_e32 v70, v70
	v_mfma_f32_16x16x32_bf16 v[44:47], v[212:215], v[192:195], v[44:47]
	ds_read_b64_tr_b16 v[208:209], v178 offset:57344
	ds_read_b64_tr_b16 v[210:211], v178 offset:61440
	v_exp_f32_e32 v71, v71
	s_waitcnt lgkmcnt(12)
	v_mfma_f32_16x16x32_bf16 v[16:19], v[230:233], v[184:187], v[16:19]
	v_exp_f32_e32 v72, v72
	v_mfma_f32_16x16x32_bf16 v[48:51], v[230:233], v[192:195], v[48:51]
	ds_read_b64_tr_b16 v[212:213], v179 offset:57344
	ds_read_b64_tr_b16 v[214:215], v179 offset:61440
	v_exp_f32_e32 v73, v73
	s_waitcnt lgkmcnt(12)
	v_mfma_f32_16x16x32_bf16 v[20:23], v[234:237], v[184:187], v[20:23]
	v_exp_f32_e32 v74, v74
	v_mfma_f32_16x16x32_bf16 v[52:55], v[234:237], v[192:195], v[52:55]
	ds_read_b64_tr_b16 v[230:231], v180 offset:57344
	ds_read_b64_tr_b16 v[232:233], v180 offset:61440
	v_exp_f32_e32 v75, v75
	s_waitcnt lgkmcnt(12)
	v_mfma_f32_16x16x32_bf16 v[24:27], v[238:241], v[184:187], v[24:27]
	v_exp_f32_e32 v76, v76
	v_mfma_f32_16x16x32_bf16 v[56:59], v[238:241], v[192:195], v[56:59]
	ds_read_b64_tr_b16 v[234:235], v182 offset:57344
	ds_read_b64_tr_b16 v[236:237], v182 offset:61440
	v_exp_f32_e32 v77, v77
	s_waitcnt lgkmcnt(12)
	v_mfma_f32_16x16x32_bf16 v[28:31], v[242:245], v[184:187], v[28:31]
	v_exp_f32_e32 v78, v78
	v_mfma_f32_16x16x32_bf16 v[60:63], v[242:245], v[192:195], v[60:63]
	ds_read_b64_tr_b16 v[238:239], v216 offset:57344
	ds_read_b64_tr_b16 v[240:241], v216 offset:61440
	v_exp_f32_e32 v79, v79
	s_waitcnt lgkmcnt(12)
	v_mfma_f32_16x16x32_bf16 v[0:3], v[200:203], v[188:191], v[0:3]
	v_exp_f32_e32 v80, v80
	v_mfma_f32_16x16x32_bf16 v[32:35], v[200:203], v[196:199], v[32:35]
	ds_read_b64_tr_b16 v[242:243], v217 offset:57344
	ds_read_b64_tr_b16 v[244:245], v217 offset:61440
	ds_read_b128 v[200:203], v172 offset:16384
	v_exp_f32_e32 v81, v81
	s_waitcnt lgkmcnt(13)
	v_mfma_f32_16x16x32_bf16 v[4:7], v[204:207], v[188:191], v[4:7]
	v_exp_f32_e32 v82, v82
	v_mfma_f32_16x16x32_bf16 v[36:39], v[204:207], v[196:199], v[36:39]
	ds_read_b128 v[204:207], v172 offset:20480
	v_exp_f32_e32 v83, v83
	s_waitcnt lgkmcnt(12)
	v_mfma_f32_16x16x32_bf16 v[8:11], v[208:211], v[188:191], v[8:11]
	v_exp_f32_e32 v84, v84
	v_mfma_f32_16x16x32_bf16 v[40:43], v[208:211], v[196:199], v[40:43]
	ds_read_b128 v[208:211], v172 offset:24576
	v_exp_f32_e32 v85, v85
	s_waitcnt lgkmcnt(11)
	v_mfma_f32_16x16x32_bf16 v[12:15], v[212:215], v[188:191], v[12:15]
	v_exp_f32_e32 v86, v86
	v_mfma_f32_16x16x32_bf16 v[44:47], v[212:215], v[196:199], v[44:47]
	ds_read_b128 v[212:215], v172 offset:28672
	v_exp_f32_e32 v87, v87
	s_waitcnt lgkmcnt(10)
	v_mfma_f32_16x16x32_bf16 v[16:19], v[230:233], v[188:191], v[16:19]
	v_exp_f32_e32 v88, v88
	v_mfma_f32_16x16x32_bf16 v[48:51], v[230:233], v[196:199], v[48:51]
	ds_read_b128 v[230:233], v173 offset:16384
	v_exp_f32_e32 v89, v89
	s_waitcnt lgkmcnt(9)
	v_mfma_f32_16x16x32_bf16 v[20:23], v[234:237], v[188:191], v[20:23]
	v_exp_f32_e32 v90, v90
	v_mfma_f32_16x16x32_bf16 v[52:55], v[234:237], v[196:199], v[52:55]
	ds_read_b128 v[234:237], v173 offset:20480
	v_exp_f32_e32 v91, v91
	s_waitcnt lgkmcnt(8)
	v_mfma_f32_16x16x32_bf16 v[24:27], v[238:241], v[188:191], v[24:27]
	v_exp_f32_e32 v92, v92
	v_mfma_f32_16x16x32_bf16 v[56:59], v[238:241], v[196:199], v[56:59]
	ds_read_b128 v[238:241], v173 offset:24576
	v_exp_f32_e32 v93, v93
	s_waitcnt lgkmcnt(7)
	v_mfma_f32_16x16x32_bf16 v[28:31], v[242:245], v[188:191], v[28:31]
	v_exp_f32_e32 v94, v94
	v_mfma_f32_16x16x32_bf16 v[60:63], v[242:245], v[196:199], v[60:63]
	ds_read_b128 v[242:245], v173 offset:28672
	v_exp_f32_e32 v95, v95
	s_waitcnt vmcnt(4)
	s_barrier
	s_add_i32 s44, s44, 1
	s_cmp_lt_u32 s44, 63
	s_cbranch_scc1 .Ldense_loop
; __device__ __forceinline__ void finishSM(f32x16& p0, f32x16& p1, float alpha, float& l_reg, bf16x8& pa0, bf16x8& pa1, bf16x8& pa2, bf16x8& pa3) {
; #pragma unroll
;   for (int r = 0; r < 16; ++r) p1[r] = __builtin_amdgcn_exp2f(p1[r]);
;   float ps = 0;
; #pragma unroll
;   for (int r = 0; r < 16; ++r) ps += p0[r];
; #pragma unroll
;   for (int r = 0; r < 16; ++r) ps += p1[r];
;   { auto rr = __builtin_amdgcn_permlane32_swap(__float_as_uint(ps), __float_as_uint(ps), false, false);
;     ps = __uint_as_float(rr[0]) + __uint_as_float(rr[1]); }
;   l_reg = l_reg * alpha + ps;
;     ...
;   PK4(p0, 0, pa0); PK4(p0, 8, pa1); PK4(p1, 0, pa2); PK4(p1, 8, pa3);
;     ...
; }
; __device__ __forceinline__ void qkt(f32x16& p0, f32x16& p1, const bf16* Ks, const bf16x8* qr, int r32, int hi) {
;   p0 = f32x16{}; p1 = f32x16{};
; #pragma unroll
;   for (int d0 = 0; d0 < 8; ++d0) { int cb = (d0 * 16 + hi * 8) * 2;
;     bf16x8 b0 = *reinterpret_cast<const bf16x8*>((const char*)Ks + KSWZ(r32, cb));
;     bf16x8 b1 = *reinterpret_cast<const bf16x8*>((const char*)Ks + KSWZ(32 + r32, cb));
;     p0 = __builtin_amdgcn_mfma_f32_32x32x16_bf16(b0, qr[d0], p0, 0, 0, 0);
;     p1 = __builtin_amdgcn_mfma_f32_32x32x16_bf16(b1, qr[d0], p1, 0, 0, 0); }
; }
; __device__ __forceinline__ int v_st(int k, int c) { const int kk = (k & ~0xC) | ((k & 4) << 1) | ((k & 8) >> 1); return ((kk >> 3) * 4 + (c >> 5)) * 512 + ((kk & 7) * 32 + (c & 31)) * 2; }
; __device__ __forceinline__ int v_rd_base(int lane) { return ((lane & 3) << 3) | (((lane >> 2) & 3) << 6) | (((lane >> 4) & 1) << 5) | (((lane >> 5) & 1) << 8); }
; template <int OFF> __device__ __forceinline__ s16x4 tr_read(int vb) {
;   s16x4 r; asm volatile("ds_read_b64_tr_b16 %0, %1 offset:%2" : "=&v"(r) : "v"(vb), "i"(OFF) : "memory"); return r;
; }
; template <int D0> __device__ __forceinline__ void pv_one(f32x16& od, int vb, bf16x8 pa0, bf16x8 pa1, bf16x8 pa2, bf16x8 pa3) {
;   const s16x4 l0 = tr_read<v_rd_off(D0, 0, 0)>(vb), h0 = tr_read<v_rd_off(D0, 0, 1)>(vb), l1 = tr_read<v_rd_off(D0, 1, 0)>(vb), h1 = tr_read<v_rd_off(D0, 1, 1)>(vb);
;   const s16x4 l2 = tr_read<v_rd_off(D0, 2, 0)>(vb), h2 = tr_read<v_rd_off(D0, 2, 1)>(vb), l3 = tr_read<v_rd_off(D0, 3, 0)>(vb), h3 = tr_read<v_rd_off(D0, 3, 1)>(vb);
;   asm volatile("s_waitcnt lgkmcnt(0)" ::: "memory"); SBAR();
;     ...
;   od = __builtin_amdgcn_mfma_f32_32x32x16_bf16(pa0, PK(l0, h0), od, 0, 0, 0);
	s_waitcnt lgkmcnt(7)
	v_mfma_f32_16x16x32_bf16 v[128:131], v[200:203], v[96:99], 0
	v_add_f32_e32 v169, v169, v64
	s_add_i32 m0, s32, 0x18000
	s_nop 0
	global_load_lds_dwordx4 v181, s[0:1]
	v_mfma_f32_16x16x32_bf16 v[132:135], v[200:203], v[112:115], 0
	ds_read_b128 v[200:203], v174 offset:16384
	v_add_f32_e32 v169, v169, v65
	v_cvt_pk_bf16_f32 v184, v64, v65
	s_waitcnt lgkmcnt(7)
	v_mfma_f32_16x16x32_bf16 v[136:139], v[204:207], v[96:99], 0
	v_add_f32_e32 v169, v169, v66
	v_mfma_f32_16x16x32_bf16 v[140:143], v[204:207], v[112:115], 0
	ds_read_b128 v[204:207], v174 offset:20480
	v_add_f32_e32 v169, v169, v67
	v_cvt_pk_bf16_f32 v185, v66, v67
	s_waitcnt lgkmcnt(7)
	v_mfma_f32_16x16x32_bf16 v[144:147], v[208:211], v[96:99], 0
	v_add_f32_e32 v222, v222, v68
	s_add_i32 m0, s32, 0x1a000
	s_nop 0
	global_load_lds_dwordx4 v181, s[4:5]
	s_add_u32 s0, s0, 0x150000
	s_addc_u32 s1, s1, 0
	s_add_u32 s4, s4, 0x150000
	s_addc_u32 s5, s5, 0
	v_mfma_f32_16x16x32_bf16 v[148:151], v[208:211], v[112:115], 0
	ds_read_b128 v[208:211], v174 offset:24576
	v_add_f32_e32 v222, v222, v69
	v_cvt_pk_bf16_f32 v186, v72, v73
	s_waitcnt lgkmcnt(7)
	v_mfma_f32_16x16x32_bf16 v[152:155], v[212:215], v[96:99], 0
	v_add_f32_e32 v222, v222, v70
	v_mfma_f32_16x16x32_bf16 v[156:159], v[212:215], v[112:115], 0
	ds_read_b128 v[212:215], v174 offset:28672
	v_add_f32_e32 v222, v222, v71
	v_cvt_pk_bf16_f32 v187, v74, v75
	s_waitcnt lgkmcnt(7)
	v_mfma_f32_16x16x32_bf16 v[128:131], v[230:233], v[100:103], v[128:131]
	v_add_f32_e32 v169, v169, v72
	v_mfma_f32_16x16x32_bf16 v[132:135], v[230:233], v[116:119], v[132:135]
	ds_read_b128 v[230:233], v175 offset:16384
	v_add_f32_e32 v169, v169, v73
	v_cvt_pk_bf16_f32 v188, v80, v81
	s_waitcnt lgkmcnt(7)
	v_mfma_f32_16x16x32_bf16 v[136:139], v[234:237], v[100:103], v[136:139]
	v_add_f32_e32 v169, v169, v74
	v_mfma_f32_16x16x32_bf16 v[140:143], v[234:237], v[116:119], v[140:143]
	ds_read_b128 v[234:237], v175 offset:20480
	v_add_f32_e32 v169, v169, v75
	v_cvt_pk_bf16_f32 v189, v82, v83
	s_waitcnt lgkmcnt(7)
	v_mfma_f32_16x16x32_bf16 v[144:147], v[238:241], v[100:103], v[144:147]
	v_add_f32_e32 v222, v222, v76
	v_mfma_f32_16x16x32_bf16 v[148:151], v[238:241], v[116:119], v[148:151]
	ds_read_b128 v[238:241], v175 offset:24576
	v_add_f32_e32 v222, v222, v77
	v_cvt_pk_bf16_f32 v190, v88, v89
	s_waitcnt lgkmcnt(7)
	v_mfma_f32_16x16x32_bf16 v[152:155], v[242:245], v[100:103], v[152:155]
	v_add_f32_e32 v222, v222, v78
	v_mfma_f32_16x16x32_bf16 v[156:159], v[242:245], v[116:119], v[156:159]
	ds_read_b128 v[242:245], v175 offset:28672
	v_add_f32_e32 v222, v222, v79
	v_cvt_pk_bf16_f32 v191, v90, v91
	s_waitcnt lgkmcnt(7)
	v_mfma_f32_16x16x32_bf16 v[128:131], v[200:203], v[104:107], v[128:131]
	v_add_f32_e32 v169, v169, v80
	v_mfma_f32_16x16x32_bf16 v[132:135], v[200:203], v[120:123], v[132:135]
	v_add_f32_e32 v169, v169, v81
	v_cvt_pk_bf16_f32 v192, v68, v69
	s_waitcnt lgkmcnt(6)
	v_mfma_f32_16x16x32_bf16 v[136:139], v[204:207], v[104:107], v[136:139]
	ds_read_b64_tr_b16 v[200:201], v176 offset:0
	ds_read_b64_tr_b16 v[202:203], v176 offset:4096
	v_add_f32_e32 v169, v169, v82
	v_mfma_f32_16x16x32_bf16 v[140:143], v[204:207], v[120:123], v[140:143]
	v_add_f32_e32 v169, v169, v83
	v_cvt_pk_bf16_f32 v193, v70, v71
	s_waitcnt lgkmcnt(7)
	v_mfma_f32_16x16x32_bf16 v[144:147], v[208:211], v[104:107], v[144:147]
	ds_read_b64_tr_b16 v[204:205], v177 offset:0
	ds_read_b64_tr_b16 v[206:207], v177 offset:4096
	v_add_f32_e32 v222, v222, v84
	v_mfma_f32_16x16x32_bf16 v[148:151], v[208:211], v[120:123], v[148:151]
	v_add_f32_e32 v222, v222, v85
	v_cvt_pk_bf16_f32 v194, v76, v77
	s_waitcnt lgkmcnt(8)
	v_mfma_f32_16x16x32_bf16 v[152:155], v[212:215], v[104:107], v[152:155]
	ds_read_b64_tr_b16 v[208:209], v178 offset:0
	ds_read_b64_tr_b16 v[210:211], v178 offset:4096
	v_add_f32_e32 v222, v222, v86
	v_mfma_f32_16x16x32_bf16 v[156:159], v[212:215], v[120:123], v[156:159]
	v_add_f32_e32 v222, v222, v87
	v_cvt_pk_bf16_f32 v195, v78, v79
	s_waitcnt lgkmcnt(9)
	v_mfma_f32_16x16x32_bf16 v[128:131], v[230:233], v[108:111], v[128:131]
	ds_read_b64_tr_b16 v[212:213], v179 offset:0
	ds_read_b64_tr_b16 v[214:215], v179 offset:4096
	v_add_f32_e32 v169, v169, v88
	v_mfma_f32_16x16x32_bf16 v[132:135], v[230:233], v[124:127], v[132:135]
	v_add_f32_e32 v169, v169, v89
	v_cvt_pk_bf16_f32 v196, v84, v85
	s_waitcnt lgkmcnt(10)
	v_mfma_f32_16x16x32_bf16 v[136:139], v[234:237], v[108:111], v[136:139]
	ds_read_b64_tr_b16 v[230:231], v180 offset:0
	ds_read_b64_tr_b16 v[232:233], v180 offset:4096
	v_add_f32_e32 v169, v169, v90
	v_mfma_f32_16x16x32_bf16 v[140:143], v[234:237], v[124:127], v[140:143]
	v_add_f32_e32 v169, v169, v91
	v_cvt_pk_bf16_f32 v197, v86, v87
	s_waitcnt lgkmcnt(11)
	v_mfma_f32_16x16x32_bf16 v[144:147], v[238:241], v[108:111], v[144:147]
	ds_read_b64_tr_b16 v[234:235], v182 offset:0
	ds_read_b64_tr_b16 v[236:237], v182 offset:4096
	v_add_f32_e32 v222, v222, v92
	v_mfma_f32_16x16x32_bf16 v[148:151], v[238:241], v[124:127], v[148:151]
	v_add_f32_e32 v222, v222, v93
	v_cvt_pk_bf16_f32 v198, v92, v93
	s_waitcnt lgkmcnt(12)
	v_mfma_f32_16x16x32_bf16 v[152:155], v[242:245], v[108:111], v[152:155]
	ds_read_b64_tr_b16 v[238:239], v216 offset:0
	ds_read_b64_tr_b16 v[240:241], v216 offset:4096
	v_add_f32_e32 v222, v222, v94
	v_mfma_f32_16x16x32_bf16 v[156:159], v[242:245], v[124:127], v[156:159]
	v_add_f32_e32 v222, v222, v95
	v_cvt_pk_bf16_f32 v199, v94, v95
	s_waitcnt lgkmcnt(12)
	v_mfma_f32_16x16x32_bf16 v[0:3], v[200:203], v[184:187], v[0:3]
	v_exp_f32_e32 v128, v128
	v_mfma_f32_16x16x32_bf16 v[32:35], v[200:203], v[192:195], v[32:35]
	ds_read_b64_tr_b16 v[242:243], v217 offset:0
	ds_read_b64_tr_b16 v[244:245], v217 offset:4096
	v_exp_f32_e32 v129, v129
	s_waitcnt lgkmcnt(12)
; __device__ __forceinline__ void finishSM(f32x16& p0, f32x16& p1, float alpha, float& l_reg, bf16x8& pa0, bf16x8& pa1, bf16x8& pa2, bf16x8& pa3) {
; #pragma unroll
;   for (int r = 0; r < 16; ++r) p1[r] = __builtin_amdgcn_exp2f(p1[r]);
;   float ps = 0;
; #pragma unroll
;   for (int r = 0; r < 16; ++r) ps += p0[r];
; #pragma unroll
;   for (int r = 0; r < 16; ++r) ps += p1[r];
;   { auto rr = __builtin_amdgcn_permlane32_swap(__float_as_uint(ps), __float_as_uint(ps), false, false);
;     ps = __uint_as_float(rr[0]) + __uint_as_float(rr[1]); }
;   l_reg = l_reg * alpha + ps;
;     ...
;   PK4(p0, 0, pa0); PK4(p0, 8, pa1); PK4(p1, 0, pa2); PK4(p1, 8, pa3);
;     ...
; }
; __device__ __forceinline__ void qkt(f32x16& p0, f32x16& p1, const bf16* Ks, const bf16x8* qr, int r32, int hi) {
;   p0 = f32x16{}; p1 = f32x16{};
; #pragma unroll
;   for (int d0 = 0; d0 < 8; ++d0) { int cb = (d0 * 16 + hi * 8) * 2;
;     bf16x8 b0 = *reinterpret_cast<const bf16x8*>((const char*)Ks + KSWZ(r32, cb));
;     bf16x8 b1 = *reinterpret_cast<const bf16x8*>((const char*)Ks + KSWZ(32 + r32, cb));
;     p0 = __builtin_amdgcn_mfma_f32_32x32x16_bf16(b0, qr[d0], p0, 0, 0, 0);
;     p1 = __builtin_amdgcn_mfma_f32_32x32x16_bf16(b1, qr[d0], p1, 0, 0, 0); }
; }
; __device__ __forceinline__ int v_st(int k, int c) { const int kk = (k & ~0xC) | ((k & 4) << 1) | ((k & 8) >> 1); return ((kk >> 3) * 4 + (c >> 5)) * 512 + ((kk & 7) * 32 + (c & 31)) * 2; }
; __device__ __forceinline__ int v_rd_base(int lane) { return ((lane & 3) << 3) | (((lane >> 2) & 3) << 6) | (((lane >> 4) & 1) << 5) | (((lane >> 5) & 1) << 8); }
; template <int OFF> __device__ __forceinline__ s16x4 tr_read(int vb) {
;   s16x4 r; asm volatile("ds_read_b64_tr_b16 %0, %1 offset:%2" : "=&v"(r) : "v"(vb), "i"(OFF) : "memory"); return r;
; }
; template <int D0> __device__ __forceinline__ void pv_one(f32x16& od, int vb, bf16x8 pa0, bf16x8 pa1, bf16x8 pa2, bf16x8 pa3) {
;   const s16x4 l0 = tr_read<v_rd_off(D0, 0, 0)>(vb), h0 = tr_read<v_rd_off(D0, 0, 1)>(vb), l1 = tr_read<v_rd_off(D0, 1, 0)>(vb), h1 = tr_read<v_rd_off(D0, 1, 1)>(vb);
;   const s16x4 l2 = tr_read<v_rd_off(D0, 2, 0)>(vb), h2 = tr_read<v_rd_off(D0, 2, 1)>(vb), l3 = tr_read<v_rd_off(D0, 3, 0)>(vb), h3 = tr_read<v_rd_off(D0, 3, 1)>(vb);
;   asm volatile("s_waitcnt lgkmcnt(0)" ::: "memory"); SBAR();
;     ...
;   od = __builtin_amdgcn_mfma_f32_32x32x16_bf16(pa0, PK(l0, h0), od, 0, 0, 0);
	v_mfma_f32_16x16x32_bf16 v[4:7], v[204:207], v[184:187], v[4:7]
	v_exp_f32_e32 v130, v130
	v_mfma_f32_16x16x32_bf16 v[36:39], v[204:207], v[192:195], v[36:39]
	ds_read_b64_tr_b16 v[200:201], v176 offset:8192
	ds_read_b64_tr_b16 v[202:203], v176 offset:12288
	v_exp_f32_e32 v131, v131
	s_waitcnt lgkmcnt(12)
	v_mfma_f32_16x16x32_bf16 v[8:11], v[208:211], v[184:187], v[8:11]
	v_exp_f32_e32 v132, v132
	v_mfma_f32_16x16x32_bf16 v[40:43], v[208:211], v[192:195], v[40:43]
	ds_read_b64_tr_b16 v[204:205], v177 offset:8192
	ds_read_b64_tr_b16 v[206:207], v177 offset:12288
	v_exp_f32_e32 v133, v133
	s_waitcnt lgkmcnt(12)
	v_mfma_f32_16x16x32_bf16 v[12:15], v[212:215], v[184:187], v[12:15]
	v_exp_f32_e32 v134, v134
	v_mfma_f32_16x16x32_bf16 v[44:47], v[212:215], v[192:195], v[44:47]
	ds_read_b64_tr_b16 v[208:209], v178 offset:8192
	ds_read_b64_tr_b16 v[210:211], v178 offset:12288
	v_exp_f32_e32 v135, v135
	s_waitcnt lgkmcnt(12)
	v_mfma_f32_16x16x32_bf16 v[16:19], v[230:233], v[184:187], v[16:19]
	v_exp_f32_e32 v136, v136
	v_mfma_f32_16x16x32_bf16 v[48:51], v[230:233], v[192:195], v[48:51]
	ds_read_b64_tr_b16 v[212:213], v179 offset:8192
	ds_read_b64_tr_b16 v[214:215], v179 offset:12288
	v_exp_f32_e32 v137, v137
	s_waitcnt lgkmcnt(12)
	v_mfma_f32_16x16x32_bf16 v[20:23], v[234:237], v[184:187], v[20:23]
	v_exp_f32_e32 v138, v138
	v_mfma_f32_16x16x32_bf16 v[52:55], v[234:237], v[192:195], v[52:55]
	ds_read_b64_tr_b16 v[230:231], v180 offset:8192
	ds_read_b64_tr_b16 v[232:233], v180 offset:12288
	v_exp_f32_e32 v139, v139
	s_waitcnt lgkmcnt(12)
	v_mfma_f32_16x16x32_bf16 v[24:27], v[238:241], v[184:187], v[24:27]
	v_exp_f32_e32 v140, v140
	v_mfma_f32_16x16x32_bf16 v[56:59], v[238:241], v[192:195], v[56:59]
	ds_read_b64_tr_b16 v[234:235], v182 offset:8192
	ds_read_b64_tr_b16 v[236:237], v182 offset:12288
	v_exp_f32_e32 v141, v141
	s_waitcnt lgkmcnt(12)
	v_mfma_f32_16x16x32_bf16 v[28:31], v[242:245], v[184:187], v[28:31]
	v_exp_f32_e32 v142, v142
	v_mfma_f32_16x16x32_bf16 v[60:63], v[242:245], v[192:195], v[60:63]
	ds_read_b64_tr_b16 v[238:239], v216 offset:8192
	ds_read_b64_tr_b16 v[240:241], v216 offset:12288
	v_exp_f32_e32 v143, v143
	s_waitcnt lgkmcnt(12)
	v_mfma_f32_16x16x32_bf16 v[0:3], v[200:203], v[188:191], v[0:3]
	v_exp_f32_e32 v144, v144
	v_mfma_f32_16x16x32_bf16 v[32:35], v[200:203], v[196:199], v[32:35]
	ds_read_b64_tr_b16 v[242:243], v217 offset:8192
	ds_read_b64_tr_b16 v[244:245], v217 offset:12288
	ds_read_b128 v[200:203], v172 offset:32768
	v_exp_f32_e32 v145, v145
	s_waitcnt lgkmcnt(13)
	v_mfma_f32_16x16x32_bf16 v[4:7], v[204:207], v[188:191], v[4:7]
	v_exp_f32_e32 v146, v146
	v_mfma_f32_16x16x32_bf16 v[36:39], v[204:207], v[196:199], v[36:39]
	ds_read_b128 v[204:207], v172 offset:36864
	v_exp_f32_e32 v147, v147
	s_waitcnt lgkmcnt(12)
	v_mfma_f32_16x16x32_bf16 v[8:11], v[208:211], v[188:191], v[8:11]
	v_exp_f32_e32 v148, v148
	v_mfma_f32_16x16x32_bf16 v[40:43], v[208:211], v[196:199], v[40:43]
	ds_read_b128 v[208:211], v172 offset:40960
	v_exp_f32_e32 v149, v149
	s_waitcnt lgkmcnt(11)
	v_mfma_f32_16x16x32_bf16 v[12:15], v[212:215], v[188:191], v[12:15]
	v_exp_f32_e32 v150, v150
	v_mfma_f32_16x16x32_bf16 v[44:47], v[212:215], v[196:199], v[44:47]
	ds_read_b128 v[212:215], v172 offset:45056
	v_exp_f32_e32 v151, v151
	s_waitcnt lgkmcnt(10)
	v_mfma_f32_16x16x32_bf16 v[16:19], v[230:233], v[188:191], v[16:19]
	v_exp_f32_e32 v152, v152
	v_mfma_f32_16x16x32_bf16 v[48:51], v[230:233], v[196:199], v[48:51]
	ds_read_b128 v[230:233], v173 offset:32768
	v_exp_f32_e32 v153, v153
	s_waitcnt lgkmcnt(9)
	v_mfma_f32_16x16x32_bf16 v[20:23], v[234:237], v[188:191], v[20:23]
	v_exp_f32_e32 v154, v154
	v_mfma_f32_16x16x32_bf16 v[52:55], v[234:237], v[196:199], v[52:55]
	ds_read_b128 v[234:237], v173 offset:36864
	v_exp_f32_e32 v155, v155
	s_waitcnt lgkmcnt(8)
	v_mfma_f32_16x16x32_bf16 v[24:27], v[238:241], v[188:191], v[24:27]
	v_exp_f32_e32 v156, v156
	v_mfma_f32_16x16x32_bf16 v[56:59], v[238:241], v[196:199], v[56:59]
	ds_read_b128 v[238:241], v173 offset:40960
	v_exp_f32_e32 v157, v157
	s_waitcnt lgkmcnt(7)
	v_mfma_f32_16x16x32_bf16 v[28:31], v[242:245], v[188:191], v[28:31]
	v_exp_f32_e32 v158, v158
	v_mfma_f32_16x16x32_bf16 v[60:63], v[242:245], v[196:199], v[60:63]
	ds_read_b128 v[242:245], v173 offset:45056
	v_exp_f32_e32 v159, v159
	s_waitcnt vmcnt(2)
	s_barrier
; __device__ __forceinline__ void finishSM(f32x16& p0, f32x16& p1, float alpha, float& l_reg, bf16x8& pa0, bf16x8& pa1, bf16x8& pa2, bf16x8& pa3) {
; #pragma unroll
;   for (int r = 0; r < 16; ++r) p1[r] = __builtin_amdgcn_exp2f(p1[r]);
;   float ps = 0;
; #pragma unroll
;   for (int r = 0; r < 16; ++r) ps += p0[r];
; #pragma unroll
;   for (int r = 0; r < 16; ++r) ps += p1[r];
;   { auto rr = __builtin_amdgcn_permlane32_swap(__float_as_uint(ps), __float_as_uint(ps), false, false);
;     ps = __uint_as_float(rr[0]) + __uint_as_float(rr[1]); }
;   l_reg = l_reg * alpha + ps;
;     ...
;   PK4(p0, 0, pa0); PK4(p0, 8, pa1); PK4(p1, 0, pa2); PK4(p1, 8, pa3);
;     ...
; }
; __device__ __forceinline__ void qkt(f32x16& p0, f32x16& p1, const bf16* Ks, const bf16x8* qr, int r32, int hi) {
;   p0 = f32x16{}; p1 = f32x16{};
; #pragma unroll
;   for (int d0 = 0; d0 < 8; ++d0) { int cb = (d0 * 16 + hi * 8) * 2;
;     bf16x8 b0 = *reinterpret_cast<const bf16x8*>((const char*)Ks + KSWZ(r32, cb));
;     bf16x8 b1 = *reinterpret_cast<const bf16x8*>((const char*)Ks + KSWZ(32 + r32, cb));
;     p0 = __builtin_amdgcn_mfma_f32_32x32x16_bf16(b0, qr[d0], p0, 0, 0, 0);
;     p1 = __builtin_amdgcn_mfma_f32_32x32x16_bf16(b1, qr[d0], p1, 0, 0, 0); }
; }
; __device__ __forceinline__ int v_st(int k, int c) { const int kk = (k & ~0xC) | ((k & 4) << 1) | ((k & 8) >> 1); return ((kk >> 3) * 4 + (c >> 5)) * 512 + ((kk & 7) * 32 + (c & 31)) * 2; }
; __device__ __forceinline__ int v_rd_base(int lane) { return ((lane & 3) << 3) | (((lane >> 2) & 3) << 6) | (((lane >> 4) & 1) << 5) | (((lane >> 5) & 1) << 8); }
; template <int OFF> __device__ __forceinline__ s16x4 tr_read(int vb) {
;   s16x4 r; asm volatile("ds_read_b64_tr_b16 %0, %1 offset:%2" : "=&v"(r) : "v"(vb), "i"(OFF) : "memory"); return r;
; }
; template <int D0> __device__ __forceinline__ void pv_one(f32x16& od, int vb, bf16x8 pa0, bf16x8 pa1, bf16x8 pa2, bf16x8 pa3) {
;   const s16x4 l0 = tr_read<v_rd_off(D0, 0, 0)>(vb), h0 = tr_read<v_rd_off(D0, 0, 1)>(vb), l1 = tr_read<v_rd_off(D0, 1, 0)>(vb), h1 = tr_read<v_rd_off(D0, 1, 1)>(vb);
;   const s16x4 l2 = tr_read<v_rd_off(D0, 2, 0)>(vb), h2 = tr_read<v_rd_off(D0, 2, 1)>(vb), l3 = tr_read<v_rd_off(D0, 3, 0)>(vb), h3 = tr_read<v_rd_off(D0, 3, 1)>(vb);
;   asm volatile("s_waitcnt lgkmcnt(0)" ::: "memory"); SBAR();
;     ...
;   od = __builtin_amdgcn_mfma_f32_32x32x16_bf16(pa0, PK(l0, h0), od, 0, 0, 0);
	s_waitcnt lgkmcnt(7)
	v_mfma_f32_16x16x32_bf16 v[64:67], v[200:203], v[96:99], 0
	v_add_f32_e32 v169, v169, v128
	s_add_i32 m0, s32, 0x1c000
	s_nop 0
	global_load_lds_dwordx4 v181, s[0:1]
	v_mfma_f32_16x16x32_bf16 v[68:71], v[200:203], v[112:115], 0
	ds_read_b128 v[200:203], v174 offset:32768
	v_add_f32_e32 v169, v169, v129
	v_cvt_pk_bf16_f32 v184, v128, v129
	s_waitcnt lgkmcnt(7)
	v_mfma_f32_16x16x32_bf16 v[72:75], v[204:207], v[96:99], 0
	v_add_f32_e32 v169, v169, v130
	v_mfma_f32_16x16x32_bf16 v[76:79], v[204:207], v[112:115], 0
	ds_read_b128 v[204:207], v174 offset:36864
	v_add_f32_e32 v169, v169, v131
	v_cvt_pk_bf16_f32 v185, v130, v131
	s_waitcnt lgkmcnt(7)
	v_mfma_f32_16x16x32_bf16 v[80:83], v[208:211], v[96:99], 0
	v_add_f32_e32 v222, v222, v132
	s_add_i32 m0, s32, 0x1e000
	s_nop 0
	global_load_lds_dwordx4 v181, s[4:5]
	s_add_u32 s0, s0, 0x150000
	s_addc_u32 s1, s1, 0
	s_add_u32 s4, s4, 0x150000
	s_addc_u32 s5, s5, 0
	v_mfma_f32_16x16x32_bf16 v[84:87], v[208:211], v[112:115], 0
	ds_read_b128 v[208:211], v174 offset:40960
	v_add_f32_e32 v222, v222, v133
	v_cvt_pk_bf16_f32 v186, v136, v137
	s_waitcnt lgkmcnt(7)
	v_mfma_f32_16x16x32_bf16 v[88:91], v[212:215], v[96:99], 0
	v_add_f32_e32 v222, v222, v134
	v_mfma_f32_16x16x32_bf16 v[92:95], v[212:215], v[112:115], 0
	ds_read_b128 v[212:215], v174 offset:45056
	v_add_f32_e32 v222, v222, v135
	v_cvt_pk_bf16_f32 v187, v138, v139
	s_waitcnt lgkmcnt(7)
	v_mfma_f32_16x16x32_bf16 v[64:67], v[230:233], v[100:103], v[64:67]
	v_add_f32_e32 v169, v169, v136
	v_mfma_f32_16x16x32_bf16 v[68:71], v[230:233], v[116:119], v[68:71]
	ds_read_b128 v[230:233], v175 offset:32768
	v_add_f32_e32 v169, v169, v137
	v_cvt_pk_bf16_f32 v188, v144, v145
	s_waitcnt lgkmcnt(7)
	v_mfma_f32_16x16x32_bf16 v[72:75], v[234:237], v[100:103], v[72:75]
	v_add_f32_e32 v169, v169, v138
	v_mfma_f32_16x16x32_bf16 v[76:79], v[234:237], v[116:119], v[76:79]
	ds_read_b128 v[234:237], v175 offset:36864
	v_add_f32_e32 v169, v169, v139
	v_cvt_pk_bf16_f32 v189, v146, v147
	s_waitcnt lgkmcnt(7)
	v_mfma_f32_16x16x32_bf16 v[80:83], v[238:241], v[100:103], v[80:83]
	v_add_f32_e32 v222, v222, v140
	v_mfma_f32_16x16x32_bf16 v[84:87], v[238:241], v[116:119], v[84:87]
	ds_read_b128 v[238:241], v175 offset:40960
	v_add_f32_e32 v222, v222, v141
	v_cvt_pk_bf16_f32 v190, v152, v153
	s_waitcnt lgkmcnt(7)
	v_mfma_f32_16x16x32_bf16 v[88:91], v[242:245], v[100:103], v[88:91]
	v_add_f32_e32 v222, v222, v142
	v_mfma_f32_16x16x32_bf16 v[92:95], v[242:245], v[116:119], v[92:95]
	ds_read_b128 v[242:245], v175 offset:45056
	v_add_f32_e32 v222, v222, v143
	v_cvt_pk_bf16_f32 v191, v154, v155
	s_waitcnt lgkmcnt(7)
	v_mfma_f32_16x16x32_bf16 v[64:67], v[200:203], v[104:107], v[64:67]
	v_add_f32_e32 v169, v169, v144
	v_mfma_f32_16x16x32_bf16 v[68:71], v[200:203], v[120:123], v[68:71]
	v_add_f32_e32 v169, v169, v145
	v_cvt_pk_bf16_f32 v192, v132, v133
	s_waitcnt lgkmcnt(6)
	v_mfma_f32_16x16x32_bf16 v[72:75], v[204:207], v[104:107], v[72:75]
	ds_read_b64_tr_b16 v[200:201], v176 offset:16384
	ds_read_b64_tr_b16 v[202:203], v176 offset:20480
	v_add_f32_e32 v169, v169, v146
	v_mfma_f32_16x16x32_bf16 v[76:79], v[204:207], v[120:123], v[76:79]
	v_add_f32_e32 v169, v169, v147
	v_cvt_pk_bf16_f32 v193, v134, v135
	s_waitcnt lgkmcnt(7)
	v_mfma_f32_16x16x32_bf16 v[80:83], v[208:211], v[104:107], v[80:83]
	ds_read_b64_tr_b16 v[204:205], v177 offset:16384
	ds_read_b64_tr_b16 v[206:207], v177 offset:20480
	v_add_f32_e32 v222, v222, v148
	v_mfma_f32_16x16x32_bf16 v[84:87], v[208:211], v[120:123], v[84:87]
	v_add_f32_e32 v222, v222, v149
	v_cvt_pk_bf16_f32 v194, v140, v141
	s_waitcnt lgkmcnt(8)
	v_mfma_f32_16x16x32_bf16 v[88:91], v[212:215], v[104:107], v[88:91]
	ds_read_b64_tr_b16 v[208:209], v178 offset:16384
	ds_read_b64_tr_b16 v[210:211], v178 offset:20480
	v_add_f32_e32 v222, v222, v150
	v_mfma_f32_16x16x32_bf16 v[92:95], v[212:215], v[120:123], v[92:95]
	v_add_f32_e32 v222, v222, v151
	v_cvt_pk_bf16_f32 v195, v142, v143
	s_waitcnt lgkmcnt(9)
	v_mfma_f32_16x16x32_bf16 v[64:67], v[230:233], v[108:111], v[64:67]
	ds_read_b64_tr_b16 v[212:213], v179 offset:16384
	ds_read_b64_tr_b16 v[214:215], v179 offset:20480
	v_add_f32_e32 v169, v169, v152
	v_mfma_f32_16x16x32_bf16 v[68:71], v[230:233], v[124:127], v[68:71]
	v_add_f32_e32 v169, v169, v153
	v_cvt_pk_bf16_f32 v196, v148, v149
	s_waitcnt lgkmcnt(10)
	v_mfma_f32_16x16x32_bf16 v[72:75], v[234:237], v[108:111], v[72:75]
	ds_read_b64_tr_b16 v[230:231], v180 offset:16384
	ds_read_b64_tr_b16 v[232:233], v180 offset:20480
	v_add_f32_e32 v169, v169, v154
	v_mfma_f32_16x16x32_bf16 v[76:79], v[234:237], v[124:127], v[76:79]
	v_add_f32_e32 v169, v169, v155
	v_cvt_pk_bf16_f32 v197, v150, v151
	s_waitcnt lgkmcnt(11)
	v_mfma_f32_16x16x32_bf16 v[80:83], v[238:241], v[108:111], v[80:83]
	ds_read_b64_tr_b16 v[234:235], v182 offset:16384
	ds_read_b64_tr_b16 v[236:237], v182 offset:20480
	v_add_f32_e32 v222, v222, v156
	v_mfma_f32_16x16x32_bf16 v[84:87], v[238:241], v[124:127], v[84:87]
	v_add_f32_e32 v222, v222, v157
	v_cvt_pk_bf16_f32 v198, v156, v157
	s_waitcnt lgkmcnt(12)
	v_mfma_f32_16x16x32_bf16 v[88:91], v[242:245], v[108:111], v[88:91]
	ds_read_b64_tr_b16 v[238:239], v216 offset:16384
	ds_read_b64_tr_b16 v[240:241], v216 offset:20480
	v_add_f32_e32 v222, v222, v158
	v_mfma_f32_16x16x32_bf16 v[92:95], v[242:245], v[124:127], v[92:95]
	v_add_f32_e32 v222, v222, v159
	v_cvt_pk_bf16_f32 v199, v158, v159
	s_waitcnt lgkmcnt(12)
	v_mfma_f32_16x16x32_bf16 v[0:3], v[200:203], v[184:187], v[0:3]
	v_exp_f32_e32 v64, v64
	v_mfma_f32_16x16x32_bf16 v[32:35], v[200:203], v[192:195], v[32:35]
	ds_read_b64_tr_b16 v[242:243], v217 offset:16384
	ds_read_b64_tr_b16 v[244:245], v217 offset:20480
	v_exp_f32_e32 v65, v65
	s_waitcnt lgkmcnt(12)
; __device__ __forceinline__ void finishSM(f32x16& p0, f32x16& p1, float alpha, float& l_reg, bf16x8& pa0, bf16x8& pa1, bf16x8& pa2, bf16x8& pa3) {
; #pragma unroll
;   for (int r = 0; r < 16; ++r) p1[r] = __builtin_amdgcn_exp2f(p1[r]);
;   float ps = 0;
; #pragma unroll
;   for (int r = 0; r < 16; ++r) ps += p0[r];
; #pragma unroll
;   for (int r = 0; r < 16; ++r) ps += p1[r];
;   { auto rr = __builtin_amdgcn_permlane32_swap(__float_as_uint(ps), __float_as_uint(ps), false, false);
;     ps = __uint_as_float(rr[0]) + __uint_as_float(rr[1]); }
;   l_reg = l_reg * alpha + ps;
;     ...
;   PK4(p0, 0, pa0); PK4(p0, 8, pa1); PK4(p1, 0, pa2); PK4(p1, 8, pa3);
;     ...
; }
; __device__ __forceinline__ void qkt(f32x16& p0, f32x16& p1, const bf16* Ks, const bf16x8* qr, int r32, int hi) {
;   p0 = f32x16{}; p1 = f32x16{};
; #pragma unroll
;   for (int d0 = 0; d0 < 8; ++d0) { int cb = (d0 * 16 + hi * 8) * 2;
;     bf16x8 b0 = *reinterpret_cast<const bf16x8*>((const char*)Ks + KSWZ(r32, cb));
;     bf16x8 b1 = *reinterpret_cast<const bf16x8*>((const char*)Ks + KSWZ(32 + r32, cb));
;     p0 = __builtin_amdgcn_mfma_f32_32x32x16_bf16(b0, qr[d0], p0, 0, 0, 0);
;     p1 = __builtin_amdgcn_mfma_f32_32x32x16_bf16(b1, qr[d0], p1, 0, 0, 0); }
; }
; __device__ __forceinline__ int v_st(int k, int c) { const int kk = (k & ~0xC) | ((k & 4) << 1) | ((k & 8) >> 1); return ((kk >> 3) * 4 + (c >> 5)) * 512 + ((kk & 7) * 32 + (c & 31)) * 2; }
; __device__ __forceinline__ int v_rd_base(int lane) { return ((lane & 3) << 3) | (((lane >> 2) & 3) << 6) | (((lane >> 4) & 1) << 5) | (((lane >> 5) & 1) << 8); }
; template <int OFF> __device__ __forceinline__ s16x4 tr_read(int vb) {
;   s16x4 r; asm volatile("ds_read_b64_tr_b16 %0, %1 offset:%2" : "=&v"(r) : "v"(vb), "i"(OFF) : "memory"); return r;
; }
; template <int D0> __device__ __forceinline__ void pv_one(f32x16& od, int vb, bf16x8 pa0, bf16x8 pa1, bf16x8 pa2, bf16x8 pa3) {
;   const s16x4 l0 = tr_read<v_rd_off(D0, 0, 0)>(vb), h0 = tr_read<v_rd_off(D0, 0, 1)>(vb), l1 = tr_read<v_rd_off(D0, 1, 0)>(vb), h1 = tr_read<v_rd_off(D0, 1, 1)>(vb);
;   const s16x4 l2 = tr_read<v_rd_off(D0, 2, 0)>(vb), h2 = tr_read<v_rd_off(D0, 2, 1)>(vb), l3 = tr_read<v_rd_off(D0, 3, 0)>(vb), h3 = tr_read<v_rd_off(D0, 3, 1)>(vb);
;   asm volatile("s_waitcnt lgkmcnt(0)" ::: "memory"); SBAR();
;     ...
;   od = __builtin_amdgcn_mfma_f32_32x32x16_bf16(pa0, PK(l0, h0), od, 0, 0, 0);
	v_mfma_f32_16x16x32_bf16 v[4:7], v[204:207], v[184:187], v[4:7]
	v_exp_f32_e32 v66, v66
	v_mfma_f32_16x16x32_bf16 v[36:39], v[204:207], v[192:195], v[36:39]
	ds_read_b64_tr_b16 v[200:201], v176 offset:24576
	ds_read_b64_tr_b16 v[202:203], v176 offset:28672
	v_exp_f32_e32 v67, v67
	s_waitcnt lgkmcnt(12)
	v_mfma_f32_16x16x32_bf16 v[8:11], v[208:211], v[184:187], v[8:11]
	v_exp_f32_e32 v68, v68
	v_mfma_f32_16x16x32_bf16 v[40:43], v[208:211], v[192:195], v[40:43]
	ds_read_b64_tr_b16 v[204:205], v177 offset:24576
	ds_read_b64_tr_b16 v[206:207], v177 offset:28672
	v_exp_f32_e32 v69, v69
	s_waitcnt lgkmcnt(12)
	v_mfma_f32_16x16x32_bf16 v[12:15], v[212:215], v[184:187], v[12:15]
	v_exp_f32_e32 v70, v70
	v_mfma_f32_16x16x32_bf16 v[44:47], v[212:215], v[192:195], v[44:47]
	ds_read_b64_tr_b16 v[208:209], v178 offset:24576
	ds_read_b64_tr_b16 v[210:211], v178 offset:28672
	v_exp_f32_e32 v71, v71
	s_waitcnt lgkmcnt(12)
	v_mfma_f32_16x16x32_bf16 v[16:19], v[230:233], v[184:187], v[16:19]
	v_exp_f32_e32 v72, v72
	v_mfma_f32_16x16x32_bf16 v[48:51], v[230:233], v[192:195], v[48:51]
	ds_read_b64_tr_b16 v[212:213], v179 offset:24576
	ds_read_b64_tr_b16 v[214:215], v179 offset:28672
	v_exp_f32_e32 v73, v73
	s_waitcnt lgkmcnt(12)
	v_mfma_f32_16x16x32_bf16 v[20:23], v[234:237], v[184:187], v[20:23]
	v_exp_f32_e32 v74, v74
	v_mfma_f32_16x16x32_bf16 v[52:55], v[234:237], v[192:195], v[52:55]
	ds_read_b64_tr_b16 v[230:231], v180 offset:24576
	ds_read_b64_tr_b16 v[232:233], v180 offset:28672
	v_exp_f32_e32 v75, v75
	s_waitcnt lgkmcnt(12)
	v_mfma_f32_16x16x32_bf16 v[24:27], v[238:241], v[184:187], v[24:27]
	v_exp_f32_e32 v76, v76
	v_mfma_f32_16x16x32_bf16 v[56:59], v[238:241], v[192:195], v[56:59]
	ds_read_b64_tr_b16 v[234:235], v182 offset:24576
	ds_read_b64_tr_b16 v[236:237], v182 offset:28672
	v_exp_f32_e32 v77, v77
	s_waitcnt lgkmcnt(12)
	v_mfma_f32_16x16x32_bf16 v[28:31], v[242:245], v[184:187], v[28:31]
	v_exp_f32_e32 v78, v78
	v_mfma_f32_16x16x32_bf16 v[60:63], v[242:245], v[192:195], v[60:63]
	ds_read_b64_tr_b16 v[238:239], v216 offset:24576
	ds_read_b64_tr_b16 v[240:241], v216 offset:28672
	v_exp_f32_e32 v79, v79
	s_waitcnt lgkmcnt(12)
	v_mfma_f32_16x16x32_bf16 v[0:3], v[200:203], v[188:191], v[0:3]
	v_exp_f32_e32 v80, v80
	v_mfma_f32_16x16x32_bf16 v[32:35], v[200:203], v[196:199], v[32:35]
	ds_read_b64_tr_b16 v[242:243], v217 offset:24576
	ds_read_b64_tr_b16 v[244:245], v217 offset:28672
	ds_read_b128 v[200:203], v172 offset:49152
	v_exp_f32_e32 v81, v81
	s_waitcnt lgkmcnt(13)
	v_mfma_f32_16x16x32_bf16 v[4:7], v[204:207], v[188:191], v[4:7]
	v_exp_f32_e32 v82, v82
	v_mfma_f32_16x16x32_bf16 v[36:39], v[204:207], v[196:199], v[36:39]
	ds_read_b128 v[204:207], v172 offset:53248
	v_exp_f32_e32 v83, v83
	s_waitcnt lgkmcnt(12)
	v_mfma_f32_16x16x32_bf16 v[8:11], v[208:211], v[188:191], v[8:11]
	v_exp_f32_e32 v84, v84
	v_mfma_f32_16x16x32_bf16 v[40:43], v[208:211], v[196:199], v[40:43]
	ds_read_b128 v[208:211], v172 offset:57344
	v_exp_f32_e32 v85, v85
	s_waitcnt lgkmcnt(11)
	v_mfma_f32_16x16x32_bf16 v[12:15], v[212:215], v[188:191], v[12:15]
	v_exp_f32_e32 v86, v86
	v_mfma_f32_16x16x32_bf16 v[44:47], v[212:215], v[196:199], v[44:47]
	ds_read_b128 v[212:215], v172 offset:61440
	v_exp_f32_e32 v87, v87
	s_waitcnt lgkmcnt(10)
	v_mfma_f32_16x16x32_bf16 v[16:19], v[230:233], v[188:191], v[16:19]
	v_exp_f32_e32 v88, v88
	v_mfma_f32_16x16x32_bf16 v[48:51], v[230:233], v[196:199], v[48:51]
	ds_read_b128 v[230:233], v173 offset:49152
	v_exp_f32_e32 v89, v89
	s_waitcnt lgkmcnt(9)
	v_mfma_f32_16x16x32_bf16 v[20:23], v[234:237], v[188:191], v[20:23]
	v_exp_f32_e32 v90, v90
	v_mfma_f32_16x16x32_bf16 v[52:55], v[234:237], v[196:199], v[52:55]
	ds_read_b128 v[234:237], v173 offset:53248
	v_exp_f32_e32 v91, v91
	s_waitcnt lgkmcnt(8)
	v_mfma_f32_16x16x32_bf16 v[24:27], v[238:241], v[188:191], v[24:27]
	v_exp_f32_e32 v92, v92
	v_mfma_f32_16x16x32_bf16 v[56:59], v[238:241], v[196:199], v[56:59]
	ds_read_b128 v[238:241], v173 offset:57344
	v_exp_f32_e32 v93, v93
	s_waitcnt lgkmcnt(7)
	v_mfma_f32_16x16x32_bf16 v[28:31], v[242:245], v[188:191], v[28:31]
	v_exp_f32_e32 v94, v94
	v_mfma_f32_16x16x32_bf16 v[60:63], v[242:245], v[196:199], v[60:63]
	ds_read_b128 v[242:245], v173 offset:61440
	v_exp_f32_e32 v95, v95
	s_waitcnt vmcnt(2)
	s_barrier
; __device__ __forceinline__ void finishSM(f32x16& p0, f32x16& p1, float alpha, float& l_reg, bf16x8& pa0, bf16x8& pa1, bf16x8& pa2, bf16x8& pa3) {
; #pragma unroll
;   for (int r = 0; r < 16; ++r) p1[r] = __builtin_amdgcn_exp2f(p1[r]);
;   float ps = 0;
; #pragma unroll
;   for (int r = 0; r < 16; ++r) ps += p0[r];
; #pragma unroll
;   for (int r = 0; r < 16; ++r) ps += p1[r];
;   { auto rr = __builtin_amdgcn_permlane32_swap(__float_as_uint(ps), __float_as_uint(ps), false, false);
;     ps = __uint_as_float(rr[0]) + __uint_as_float(rr[1]); }
;   l_reg = l_reg * alpha + ps;
;     ...
;   PK4(p0, 0, pa0); PK4(p0, 8, pa1); PK4(p1, 0, pa2); PK4(p1, 8, pa3);
;     ...
; }
; __device__ __forceinline__ void qkt(f32x16& p0, f32x16& p1, const bf16* Ks, const bf16x8* qr, int r32, int hi) {
;   p0 = f32x16{}; p1 = f32x16{};
; #pragma unroll
;   for (int d0 = 0; d0 < 8; ++d0) { int cb = (d0 * 16 + hi * 8) * 2;
;     bf16x8 b0 = *reinterpret_cast<const bf16x8*>((const char*)Ks + KSWZ(r32, cb));
;     bf16x8 b1 = *reinterpret_cast<const bf16x8*>((const char*)Ks + KSWZ(32 + r32, cb));
;     p0 = __builtin_amdgcn_mfma_f32_32x32x16_bf16(b0, qr[d0], p0, 0, 0, 0);
;     p1 = __builtin_amdgcn_mfma_f32_32x32x16_bf16(b1, qr[d0], p1, 0, 0, 0); }
; }
; __device__ __forceinline__ int v_st(int k, int c) { const int kk = (k & ~0xC) | ((k & 4) << 1) | ((k & 8) >> 1); return ((kk >> 3) * 4 + (c >> 5)) * 512 + ((kk & 7) * 32 + (c & 31)) * 2; }
; __device__ __forceinline__ int v_rd_base(int lane) { return ((lane & 3) << 3) | (((lane >> 2) & 3) << 6) | (((lane >> 4) & 1) << 5) | (((lane >> 5) & 1) << 8); }
; template <int OFF> __device__ __forceinline__ s16x4 tr_read(int vb) {
;   s16x4 r; asm volatile("ds_read_b64_tr_b16 %0, %1 offset:%2" : "=&v"(r) : "v"(vb), "i"(OFF) : "memory"); return r;
; }
; template <int D0> __device__ __forceinline__ void pv_one(f32x16& od, int vb, bf16x8 pa0, bf16x8 pa1, bf16x8 pa2, bf16x8 pa3) {
;   const s16x4 l0 = tr_read<v_rd_off(D0, 0, 0)>(vb), h0 = tr_read<v_rd_off(D0, 0, 1)>(vb), l1 = tr_read<v_rd_off(D0, 1, 0)>(vb), h1 = tr_read<v_rd_off(D0, 1, 1)>(vb);
;   const s16x4 l2 = tr_read<v_rd_off(D0, 2, 0)>(vb), h2 = tr_read<v_rd_off(D0, 2, 1)>(vb), l3 = tr_read<v_rd_off(D0, 3, 0)>(vb), h3 = tr_read<v_rd_off(D0, 3, 1)>(vb);
;   asm volatile("s_waitcnt lgkmcnt(0)" ::: "memory"); SBAR();
;     ...
;   od = __builtin_amdgcn_mfma_f32_32x32x16_bf16(pa0, PK(l0, h0), od, 0, 0, 0);
	s_waitcnt lgkmcnt(7)
	v_mfma_f32_16x16x32_bf16 v[128:131], v[200:203], v[96:99], 0
	v_add_f32_e32 v169, v169, v64
	v_mfma_f32_16x16x32_bf16 v[132:135], v[200:203], v[112:115], 0
	ds_read_b128 v[200:203], v174 offset:49152
	v_add_f32_e32 v169, v169, v65
	v_cvt_pk_bf16_f32 v184, v64, v65
	s_waitcnt lgkmcnt(7)
	v_mfma_f32_16x16x32_bf16 v[136:139], v[204:207], v[96:99], 0
	v_add_f32_e32 v169, v169, v66
	v_mfma_f32_16x16x32_bf16 v[140:143], v[204:207], v[112:115], 0
	ds_read_b128 v[204:207], v174 offset:53248
	v_add_f32_e32 v169, v169, v67
	v_cvt_pk_bf16_f32 v185, v66, v67
	s_waitcnt lgkmcnt(7)
	v_mfma_f32_16x16x32_bf16 v[144:147], v[208:211], v[96:99], 0
	v_add_f32_e32 v222, v222, v68
	v_mfma_f32_16x16x32_bf16 v[148:151], v[208:211], v[112:115], 0
	ds_read_b128 v[208:211], v174 offset:57344
	v_add_f32_e32 v222, v222, v69
	v_cvt_pk_bf16_f32 v186, v72, v73
	s_waitcnt lgkmcnt(7)
	v_mfma_f32_16x16x32_bf16 v[152:155], v[212:215], v[96:99], 0
	v_add_f32_e32 v222, v222, v70
	v_mfma_f32_16x16x32_bf16 v[156:159], v[212:215], v[112:115], 0
	ds_read_b128 v[212:215], v174 offset:61440
	v_add_f32_e32 v222, v222, v71
	v_cvt_pk_bf16_f32 v187, v74, v75
	s_waitcnt lgkmcnt(7)
	v_mfma_f32_16x16x32_bf16 v[128:131], v[230:233], v[100:103], v[128:131]
	v_add_f32_e32 v169, v169, v72
	v_mfma_f32_16x16x32_bf16 v[132:135], v[230:233], v[116:119], v[132:135]
	ds_read_b128 v[230:233], v175 offset:49152
	v_add_f32_e32 v169, v169, v73
	v_cvt_pk_bf16_f32 v188, v80, v81
	s_waitcnt lgkmcnt(7)
	v_mfma_f32_16x16x32_bf16 v[136:139], v[234:237], v[100:103], v[136:139]
	v_add_f32_e32 v169, v169, v74
	v_mfma_f32_16x16x32_bf16 v[140:143], v[234:237], v[116:119], v[140:143]
	ds_read_b128 v[234:237], v175 offset:53248
	v_add_f32_e32 v169, v169, v75
	v_cvt_pk_bf16_f32 v189, v82, v83
	s_waitcnt lgkmcnt(7)
	v_mfma_f32_16x16x32_bf16 v[144:147], v[238:241], v[100:103], v[144:147]
	v_add_f32_e32 v222, v222, v76
	v_mfma_f32_16x16x32_bf16 v[148:151], v[238:241], v[116:119], v[148:151]
	ds_read_b128 v[238:241], v175 offset:57344
	v_add_f32_e32 v222, v222, v77
	v_cvt_pk_bf16_f32 v190, v88, v89
	s_waitcnt lgkmcnt(7)
	v_mfma_f32_16x16x32_bf16 v[152:155], v[242:245], v[100:103], v[152:155]
	v_add_f32_e32 v222, v222, v78
	v_mfma_f32_16x16x32_bf16 v[156:159], v[242:245], v[116:119], v[156:159]
	ds_read_b128 v[242:245], v175 offset:61440
	v_add_f32_e32 v222, v222, v79
	v_cvt_pk_bf16_f32 v191, v90, v91
	s_waitcnt lgkmcnt(7)
	v_mfma_f32_16x16x32_bf16 v[128:131], v[200:203], v[104:107], v[128:131]
	v_add_f32_e32 v169, v169, v80
	v_mfma_f32_16x16x32_bf16 v[132:135], v[200:203], v[120:123], v[132:135]
	v_add_f32_e32 v169, v169, v81
	v_cvt_pk_bf16_f32 v192, v68, v69
	s_waitcnt lgkmcnt(6)
	v_mfma_f32_16x16x32_bf16 v[136:139], v[204:207], v[104:107], v[136:139]
	ds_read_b64_tr_b16 v[200:201], v176 offset:32768
	ds_read_b64_tr_b16 v[202:203], v176 offset:36864
	v_add_f32_e32 v169, v169, v82
	v_mfma_f32_16x16x32_bf16 v[140:143], v[204:207], v[120:123], v[140:143]
	v_add_f32_e32 v169, v169, v83
	v_cvt_pk_bf16_f32 v193, v70, v71
	s_waitcnt lgkmcnt(7)
	v_mfma_f32_16x16x32_bf16 v[144:147], v[208:211], v[104:107], v[144:147]
	ds_read_b64_tr_b16 v[204:205], v177 offset:32768
	ds_read_b64_tr_b16 v[206:207], v177 offset:36864
	v_add_f32_e32 v222, v222, v84
	v_mfma_f32_16x16x32_bf16 v[148:151], v[208:211], v[120:123], v[148:151]
	v_add_f32_e32 v222, v222, v85
	v_cvt_pk_bf16_f32 v194, v76, v77
	s_waitcnt lgkmcnt(8)
	v_mfma_f32_16x16x32_bf16 v[152:155], v[212:215], v[104:107], v[152:155]
	ds_read_b64_tr_b16 v[208:209], v178 offset:32768
	ds_read_b64_tr_b16 v[210:211], v178 offset:36864
	v_add_f32_e32 v222, v222, v86
	v_mfma_f32_16x16x32_bf16 v[156:159], v[212:215], v[120:123], v[156:159]
	v_add_f32_e32 v222, v222, v87
	v_cvt_pk_bf16_f32 v195, v78, v79
	s_waitcnt lgkmcnt(9)
	v_mfma_f32_16x16x32_bf16 v[128:131], v[230:233], v[108:111], v[128:131]
	ds_read_b64_tr_b16 v[212:213], v179 offset:32768
	ds_read_b64_tr_b16 v[214:215], v179 offset:36864
	v_add_f32_e32 v169, v169, v88
	v_mfma_f32_16x16x32_bf16 v[132:135], v[230:233], v[124:127], v[132:135]
	v_add_f32_e32 v169, v169, v89
	v_cvt_pk_bf16_f32 v196, v84, v85
	s_waitcnt lgkmcnt(10)
	v_mfma_f32_16x16x32_bf16 v[136:139], v[234:237], v[108:111], v[136:139]
	ds_read_b64_tr_b16 v[230:231], v180 offset:32768
	ds_read_b64_tr_b16 v[232:233], v180 offset:36864
	v_add_f32_e32 v169, v169, v90
	v_mfma_f32_16x16x32_bf16 v[140:143], v[234:237], v[124:127], v[140:143]
	v_add_f32_e32 v169, v169, v91
	v_cvt_pk_bf16_f32 v197, v86, v87
	s_waitcnt lgkmcnt(11)
	v_mfma_f32_16x16x32_bf16 v[144:147], v[238:241], v[108:111], v[144:147]
	ds_read_b64_tr_b16 v[234:235], v182 offset:32768
	ds_read_b64_tr_b16 v[236:237], v182 offset:36864
	v_add_f32_e32 v222, v222, v92
	v_mfma_f32_16x16x32_bf16 v[148:151], v[238:241], v[124:127], v[148:151]
	v_add_f32_e32 v222, v222, v93
	v_cvt_pk_bf16_f32 v198, v92, v93
	s_waitcnt lgkmcnt(12)
	v_mfma_f32_16x16x32_bf16 v[152:155], v[242:245], v[108:111], v[152:155]
	ds_read_b64_tr_b16 v[238:239], v216 offset:32768
	ds_read_b64_tr_b16 v[240:241], v216 offset:36864
	v_add_f32_e32 v222, v222, v94
	v_mfma_f32_16x16x32_bf16 v[156:159], v[242:245], v[124:127], v[156:159]
	v_add_f32_e32 v222, v222, v95
	v_cvt_pk_bf16_f32 v199, v94, v95
	s_waitcnt lgkmcnt(12)
	v_mfma_f32_16x16x32_bf16 v[0:3], v[200:203], v[184:187], v[0:3]
	v_exp_f32_e32 v128, v128
	v_mfma_f32_16x16x32_bf16 v[32:35], v[200:203], v[192:195], v[32:35]
	ds_read_b64_tr_b16 v[242:243], v217 offset:32768
	ds_read_b64_tr_b16 v[244:245], v217 offset:36864
	v_exp_f32_e32 v129, v129
	s_waitcnt lgkmcnt(12)
; #define SBAR() __builtin_amdgcn_sched_barrier(0)
; __device__ __forceinline__ void finishSM(f32x16& p0, f32x16& p1, float alpha, float& l_reg, bf16x8& pa0, bf16x8& pa1, bf16x8& pa2, bf16x8& pa3) {
; #pragma unroll
;   for (int r = 0; r < 16; ++r) p1[r] = __builtin_amdgcn_exp2f(p1[r]);
;   float ps = 0;
; #pragma unroll
;   for (int r = 0; r < 16; ++r) ps += p0[r];
; #pragma unroll
;   for (int r = 0; r < 16; ++r) ps += p1[r];
;   { auto rr = __builtin_amdgcn_permlane32_swap(__float_as_uint(ps), __float_as_uint(ps), false, false);
;     ps = __uint_as_float(rr[0]) + __uint_as_float(rr[1]); }
;   l_reg = l_reg * alpha + ps;
;     ...
;   PK4(p0, 0, pa0); PK4(p0, 8, pa1); PK4(p1, 0, pa2); PK4(p1, 8, pa3);
;     ...
; }
; __device__ __forceinline__ void qkt(f32x16& p0, f32x16& p1, const bf16* Ks, const bf16x8* qr, int r32, int hi) {
;   p0 = f32x16{}; p1 = f32x16{};
; #pragma unroll
;   for (int d0 = 0; d0 < 8; ++d0) { int cb = (d0 * 16 + hi * 8) * 2;
;     bf16x8 b0 = *reinterpret_cast<const bf16x8*>((const char*)Ks + KSWZ(r32, cb));
;     bf16x8 b1 = *reinterpret_cast<const bf16x8*>((const char*)Ks + KSWZ(32 + r32, cb));
;     p0 = __builtin_amdgcn_mfma_f32_32x32x16_bf16(b0, qr[d0], p0, 0, 0, 0);
;     p1 = __builtin_amdgcn_mfma_f32_32x32x16_bf16(b1, qr[d0], p1, 0, 0, 0); }
; }
; __device__ __forceinline__ int v_st(int k, int c) { const int kk = (k & ~0xC) | ((k & 4) << 1) | ((k & 8) >> 1); return ((kk >> 3) * 4 + (c >> 5)) * 512 + ((kk & 7) * 32 + (c & 31)) * 2; }
; __device__ __forceinline__ int v_rd_base(int lane) { return ((lane & 3) << 3) | (((lane >> 2) & 3) << 6) | (((lane >> 4) & 1) << 5) | (((lane >> 5) & 1) << 8); }
; template <int OFF> __device__ __forceinline__ s16x4 tr_read(int vb) {
;   s16x4 r; asm volatile("ds_read_b64_tr_b16 %0, %1 offset:%2" : "=&v"(r) : "v"(vb), "i"(OFF) : "memory"); return r;
; }
; template <int D0> __device__ __forceinline__ void pv_one(f32x16& od, int vb, bf16x8 pa0, bf16x8 pa1, bf16x8 pa2, bf16x8 pa3) {
;     ...
;   { SBAR(); qkt(pB0, pB1, KSUB(1, 1), qr, r32, hi);
;     finishSM(pA0, pA1, alA, l_reg, pa0, pa1, pa2, pa3); SBAR();
;     pv_d0(o, VSUB(1, 0), pa0, pa1, pa2, pa3); partialSM(pB0, pB1, m_reg, mnB, alB);
;     RESC(alB);
;     finishSM(pB0, pB1, alB, l_reg, pa0, pa1, pa2, pa3); SBAR();
;     pv_d0(o, VSUB(1, 1), pa0, pa1, pa2, pa3); }
	v_mfma_f32_16x16x32_bf16 v[4:7], v[204:207], v[184:187], v[4:7]
	v_exp_f32_e32 v130, v130
	v_mfma_f32_16x16x32_bf16 v[36:39], v[204:207], v[192:195], v[36:39]
	ds_read_b64_tr_b16 v[200:201], v176 offset:40960
	ds_read_b64_tr_b16 v[202:203], v176 offset:45056
	v_exp_f32_e32 v131, v131
	s_waitcnt lgkmcnt(12)
	v_mfma_f32_16x16x32_bf16 v[8:11], v[208:211], v[184:187], v[8:11]
	v_exp_f32_e32 v132, v132
	v_mfma_f32_16x16x32_bf16 v[40:43], v[208:211], v[192:195], v[40:43]
	ds_read_b64_tr_b16 v[204:205], v177 offset:40960
	ds_read_b64_tr_b16 v[206:207], v177 offset:45056
	v_exp_f32_e32 v133, v133
	s_waitcnt lgkmcnt(12)
	v_mfma_f32_16x16x32_bf16 v[12:15], v[212:215], v[184:187], v[12:15]
	v_exp_f32_e32 v134, v134
	v_mfma_f32_16x16x32_bf16 v[44:47], v[212:215], v[192:195], v[44:47]
	ds_read_b64_tr_b16 v[208:209], v178 offset:40960
	ds_read_b64_tr_b16 v[210:211], v178 offset:45056
	v_exp_f32_e32 v135, v135
	s_waitcnt lgkmcnt(12)
	v_mfma_f32_16x16x32_bf16 v[16:19], v[230:233], v[184:187], v[16:19]
	v_exp_f32_e32 v136, v136
	v_mfma_f32_16x16x32_bf16 v[48:51], v[230:233], v[192:195], v[48:51]
	ds_read_b64_tr_b16 v[212:213], v179 offset:40960
	ds_read_b64_tr_b16 v[214:215], v179 offset:45056
	v_exp_f32_e32 v137, v137
	s_waitcnt lgkmcnt(12)
	v_mfma_f32_16x16x32_bf16 v[20:23], v[234:237], v[184:187], v[20:23]
	v_exp_f32_e32 v138, v138
	v_mfma_f32_16x16x32_bf16 v[52:55], v[234:237], v[192:195], v[52:55]
	ds_read_b64_tr_b16 v[230:231], v180 offset:40960
	ds_read_b64_tr_b16 v[232:233], v180 offset:45056
	v_exp_f32_e32 v139, v139
	s_waitcnt lgkmcnt(12)
	v_mfma_f32_16x16x32_bf16 v[24:27], v[238:241], v[184:187], v[24:27]
	v_exp_f32_e32 v140, v140
	v_mfma_f32_16x16x32_bf16 v[56:59], v[238:241], v[192:195], v[56:59]
	ds_read_b64_tr_b16 v[234:235], v182 offset:40960
	ds_read_b64_tr_b16 v[236:237], v182 offset:45056
	v_exp_f32_e32 v141, v141
	s_waitcnt lgkmcnt(12)
	v_mfma_f32_16x16x32_bf16 v[28:31], v[242:245], v[184:187], v[28:31]
	v_exp_f32_e32 v142, v142
	v_mfma_f32_16x16x32_bf16 v[60:63], v[242:245], v[192:195], v[60:63]
	ds_read_b64_tr_b16 v[238:239], v216 offset:40960
	ds_read_b64_tr_b16 v[240:241], v216 offset:45056
	v_exp_f32_e32 v143, v143
	s_waitcnt lgkmcnt(12)
	v_mfma_f32_16x16x32_bf16 v[0:3], v[200:203], v[188:191], v[0:3]
	v_exp_f32_e32 v144, v144
	v_mfma_f32_16x16x32_bf16 v[32:35], v[200:203], v[196:199], v[32:35]
	ds_read_b64_tr_b16 v[242:243], v217 offset:40960
	ds_read_b64_tr_b16 v[244:245], v217 offset:45056
	v_exp_f32_e32 v145, v145
	s_waitcnt lgkmcnt(12)
	v_mfma_f32_16x16x32_bf16 v[4:7], v[204:207], v[188:191], v[4:7]
	v_exp_f32_e32 v146, v146
	v_mfma_f32_16x16x32_bf16 v[36:39], v[204:207], v[196:199], v[36:39]
	v_exp_f32_e32 v147, v147
	s_waitcnt lgkmcnt(10)
	v_mfma_f32_16x16x32_bf16 v[8:11], v[208:211], v[188:191], v[8:11]
	v_exp_f32_e32 v148, v148
	v_mfma_f32_16x16x32_bf16 v[40:43], v[208:211], v[196:199], v[40:43]
	v_exp_f32_e32 v149, v149
	s_waitcnt lgkmcnt(8)
	v_mfma_f32_16x16x32_bf16 v[12:15], v[212:215], v[188:191], v[12:15]
	v_exp_f32_e32 v150, v150
	v_mfma_f32_16x16x32_bf16 v[44:47], v[212:215], v[196:199], v[44:47]
	v_exp_f32_e32 v151, v151
	s_waitcnt lgkmcnt(6)
	v_mfma_f32_16x16x32_bf16 v[16:19], v[230:233], v[188:191], v[16:19]
	v_exp_f32_e32 v152, v152
	v_mfma_f32_16x16x32_bf16 v[48:51], v[230:233], v[196:199], v[48:51]
	v_exp_f32_e32 v153, v153
	s_waitcnt lgkmcnt(4)
	v_mfma_f32_16x16x32_bf16 v[20:23], v[234:237], v[188:191], v[20:23]
	v_exp_f32_e32 v154, v154
	v_mfma_f32_16x16x32_bf16 v[52:55], v[234:237], v[196:199], v[52:55]
	v_exp_f32_e32 v155, v155
	s_waitcnt lgkmcnt(2)
	v_mfma_f32_16x16x32_bf16 v[24:27], v[238:241], v[188:191], v[24:27]
	v_exp_f32_e32 v156, v156
	v_mfma_f32_16x16x32_bf16 v[56:59], v[238:241], v[196:199], v[56:59]
	v_exp_f32_e32 v157, v157
	s_waitcnt lgkmcnt(0)
	v_mfma_f32_16x16x32_bf16 v[28:31], v[242:245], v[188:191], v[28:31]
	v_exp_f32_e32 v158, v158
	v_mfma_f32_16x16x32_bf16 v[60:63], v[242:245], v[196:199], v[60:63]
	v_exp_f32_e32 v159, v159
	s_waitcnt lgkmcnt(0)
	s_waitcnt vmcnt(0)
	s_barrier
	v_add_f32_e32 v169, v169, v128
	v_add_f32_e32 v169, v169, v129
	v_cvt_pk_bf16_f32 v184, v128, v129
	v_add_f32_e32 v169, v169, v130
	v_add_f32_e32 v169, v169, v131
	v_cvt_pk_bf16_f32 v185, v130, v131
	v_add_f32_e32 v222, v222, v132
	v_add_f32_e32 v222, v222, v133
	v_cvt_pk_bf16_f32 v186, v136, v137
	v_add_f32_e32 v222, v222, v134
	v_add_f32_e32 v222, v222, v135
	v_cvt_pk_bf16_f32 v187, v138, v139
	v_add_f32_e32 v169, v169, v136
	v_add_f32_e32 v169, v169, v137
	v_cvt_pk_bf16_f32 v188, v144, v145
	v_add_f32_e32 v169, v169, v138
	v_add_f32_e32 v169, v169, v139
	v_cvt_pk_bf16_f32 v189, v146, v147
	v_add_f32_e32 v222, v222, v140
	v_add_f32_e32 v222, v222, v141
	v_cvt_pk_bf16_f32 v190, v152, v153
	v_add_f32_e32 v222, v222, v142
	v_add_f32_e32 v222, v222, v143
	v_cvt_pk_bf16_f32 v191, v154, v155
	v_add_f32_e32 v169, v169, v144
	v_add_f32_e32 v169, v169, v145
	v_cvt_pk_bf16_f32 v192, v132, v133
	ds_read_b64_tr_b16 v[200:201], v176 offset:49152
	ds_read_b64_tr_b16 v[202:203], v176 offset:53248
	v_add_f32_e32 v169, v169, v146
	v_add_f32_e32 v169, v169, v147
	v_cvt_pk_bf16_f32 v193, v134, v135
	ds_read_b64_tr_b16 v[204:205], v177 offset:49152
	ds_read_b64_tr_b16 v[206:207], v177 offset:53248
	v_add_f32_e32 v222, v222, v148
	v_add_f32_e32 v222, v222, v149
	v_cvt_pk_bf16_f32 v194, v140, v141
	ds_read_b64_tr_b16 v[208:209], v178 offset:49152
	ds_read_b64_tr_b16 v[210:211], v178 offset:53248
	v_add_f32_e32 v222, v222, v150
	v_add_f32_e32 v222, v222, v151
	v_cvt_pk_bf16_f32 v195, v142, v143
	ds_read_b64_tr_b16 v[212:213], v179 offset:49152
	ds_read_b64_tr_b16 v[214:215], v179 offset:53248
	v_add_f32_e32 v169, v169, v152
	v_add_f32_e32 v169, v169, v153
	v_cvt_pk_bf16_f32 v196, v148, v149
	ds_read_b64_tr_b16 v[230:231], v180 offset:49152
	ds_read_b64_tr_b16 v[232:233], v180 offset:53248
	v_add_f32_e32 v169, v169, v154
	v_add_f32_e32 v169, v169, v155
	v_cvt_pk_bf16_f32 v197, v150, v151
	ds_read_b64_tr_b16 v[234:235], v182 offset:49152
	ds_read_b64_tr_b16 v[236:237], v182 offset:53248
	v_add_f32_e32 v222, v222, v156
	v_add_f32_e32 v222, v222, v157
	v_cvt_pk_bf16_f32 v198, v156, v157
	ds_read_b64_tr_b16 v[238:239], v216 offset:49152
	ds_read_b64_tr_b16 v[240:241], v216 offset:53248
	v_add_f32_e32 v222, v222, v158
	v_add_f32_e32 v222, v222, v159
	v_cvt_pk_bf16_f32 v199, v158, v159
	s_waitcnt lgkmcnt(12)
; #define SBAR() __builtin_amdgcn_sched_barrier(0)
; #define RESC(a) do { if (__any((a) < 1.f)) { if (hi == 0) al_l[r32] = (a); asm volatile("s_waitcnt lgkmcnt(0)" ::: "memory"); \
;     _Pragma("unroll") for (int d = 0; d < 4; ++d) _Pragma("unroll") for (int r = 0; r < 16; ++r) o[d][r] *= al_l[crow(r, hi)]; } } while (0)
; template <int D0> __device__ __forceinline__ void pv_one(f32x16& od, int vb, bf16x8 pa0, bf16x8 pa1, bf16x8 pa2, bf16x8 pa3) {
;   const s16x4 l0 = tr_read<v_rd_off(D0, 0, 0)>(vb), h0 = tr_read<v_rd_off(D0, 0, 1)>(vb), l1 = tr_read<v_rd_off(D0, 1, 0)>(vb), h1 = tr_read<v_rd_off(D0, 1, 1)>(vb);
;   const s16x4 l2 = tr_read<v_rd_off(D0, 2, 0)>(vb), h2 = tr_read<v_rd_off(D0, 2, 1)>(vb), l3 = tr_read<v_rd_off(D0, 3, 0)>(vb), h3 = tr_read<v_rd_off(D0, 3, 1)>(vb);
;   asm volatile("s_waitcnt lgkmcnt(0)" ::: "memory"); SBAR();
;     ...
;   od = __builtin_amdgcn_mfma_f32_32x32x16_bf16(pa0, PK(l0, h0), od, 0, 0, 0);
;   od = __builtin_amdgcn_mfma_f32_32x32x16_bf16(pa1, PK(l1, h1), od, 0, 0, 0);
;   od = __builtin_amdgcn_mfma_f32_32x32x16_bf16(pa2, PK(l2, h2), od, 0, 0, 0);
;   od = __builtin_amdgcn_mfma_f32_32x32x16_bf16(pa3, PK(l3, h3), od, 0, 0, 0);
;     ...
; }
; __device__ __forceinline__ void pv_d0(f32x16* o, int vb, bf16x8 pa0, bf16x8 pa1, bf16x8 pa2, bf16x8 pa3) {
;   pv_one<0>(o[0], vb, pa0, pa1, pa2, pa3); pv_one<1>(o[1], vb, pa0, pa1, pa2, pa3); pv_one<2>(o[2], vb, pa0, pa1, pa2, pa3); pv_one<3>(o[3], vb, pa0, pa1, pa2, pa3);
;     ...
;   { SBAR(); qkt(pB0, pB1, KSUB(1, 1), qr, r32, hi);
;     finishSM(pA0, pA1, alA, l_reg, pa0, pa1, pa2, pa3); SBAR();
;     pv_d0(o, VSUB(1, 0), pa0, pa1, pa2, pa3); partialSM(pB0, pB1, m_reg, mnB, alB);
;     RESC(alB);
;     finishSM(pB0, pB1, alB, l_reg, pa0, pa1, pa2, pa3); SBAR();
;     pv_d0(o, VSUB(1, 1), pa0, pa1, pa2, pa3); }
	v_mfma_f32_16x16x32_bf16 v[0:3], v[200:203], v[184:187], v[0:3]
	v_mfma_f32_16x16x32_bf16 v[32:35], v[200:203], v[192:195], v[32:35]
	ds_read_b64_tr_b16 v[242:243], v217 offset:49152
	ds_read_b64_tr_b16 v[244:245], v217 offset:53248
	s_waitcnt lgkmcnt(12)
	v_mfma_f32_16x16x32_bf16 v[4:7], v[204:207], v[184:187], v[4:7]
	v_mfma_f32_16x16x32_bf16 v[36:39], v[204:207], v[192:195], v[36:39]
	ds_read_b64_tr_b16 v[200:201], v176 offset:57344
	ds_read_b64_tr_b16 v[202:203], v176 offset:61440
	s_waitcnt lgkmcnt(12)
	v_mfma_f32_16x16x32_bf16 v[8:11], v[208:211], v[184:187], v[8:11]
	v_mfma_f32_16x16x32_bf16 v[40:43], v[208:211], v[192:195], v[40:43]
	ds_read_b64_tr_b16 v[204:205], v177 offset:57344
	ds_read_b64_tr_b16 v[206:207], v177 offset:61440
	s_waitcnt lgkmcnt(12)
	v_mfma_f32_16x16x32_bf16 v[12:15], v[212:215], v[184:187], v[12:15]
	v_mfma_f32_16x16x32_bf16 v[44:47], v[212:215], v[192:195], v[44:47]
	ds_read_b64_tr_b16 v[208:209], v178 offset:57344
	ds_read_b64_tr_b16 v[210:211], v178 offset:61440
	s_waitcnt lgkmcnt(12)
	v_mfma_f32_16x16x32_bf16 v[16:19], v[230:233], v[184:187], v[16:19]
	v_mfma_f32_16x16x32_bf16 v[48:51], v[230:233], v[192:195], v[48:51]
	ds_read_b64_tr_b16 v[212:213], v179 offset:57344
	ds_read_b64_tr_b16 v[214:215], v179 offset:61440
	s_waitcnt lgkmcnt(12)
	v_mfma_f32_16x16x32_bf16 v[20:23], v[234:237], v[184:187], v[20:23]
	v_mfma_f32_16x16x32_bf16 v[52:55], v[234:237], v[192:195], v[52:55]
	ds_read_b64_tr_b16 v[230:231], v180 offset:57344
	ds_read_b64_tr_b16 v[232:233], v180 offset:61440
	s_waitcnt lgkmcnt(12)
	v_mfma_f32_16x16x32_bf16 v[24:27], v[238:241], v[184:187], v[24:27]
	v_mfma_f32_16x16x32_bf16 v[56:59], v[238:241], v[192:195], v[56:59]
	ds_read_b64_tr_b16 v[234:235], v182 offset:57344
	ds_read_b64_tr_b16 v[236:237], v182 offset:61440
	s_waitcnt lgkmcnt(12)
	v_mfma_f32_16x16x32_bf16 v[28:31], v[242:245], v[184:187], v[28:31]
	v_mfma_f32_16x16x32_bf16 v[60:63], v[242:245], v[192:195], v[60:63]
	ds_read_b64_tr_b16 v[238:239], v216 offset:57344
	ds_read_b64_tr_b16 v[240:241], v216 offset:61440
	s_waitcnt lgkmcnt(12)
	v_mfma_f32_16x16x32_bf16 v[0:3], v[200:203], v[188:191], v[0:3]
	v_mfma_f32_16x16x32_bf16 v[32:35], v[200:203], v[196:199], v[32:35]
	ds_read_b64_tr_b16 v[242:243], v217 offset:57344
	ds_read_b64_tr_b16 v[244:245], v217 offset:61440
	s_waitcnt lgkmcnt(12)
	v_mfma_f32_16x16x32_bf16 v[4:7], v[204:207], v[188:191], v[4:7]
	v_mfma_f32_16x16x32_bf16 v[36:39], v[204:207], v[196:199], v[36:39]
	s_waitcnt lgkmcnt(10)
	v_mfma_f32_16x16x32_bf16 v[8:11], v[208:211], v[188:191], v[8:11]
	v_mfma_f32_16x16x32_bf16 v[40:43], v[208:211], v[196:199], v[40:43]
	s_waitcnt lgkmcnt(8)
	v_mfma_f32_16x16x32_bf16 v[12:15], v[212:215], v[188:191], v[12:15]
	v_mfma_f32_16x16x32_bf16 v[44:47], v[212:215], v[196:199], v[44:47]
	s_waitcnt lgkmcnt(6)
	v_mfma_f32_16x16x32_bf16 v[16:19], v[230:233], v[188:191], v[16:19]
	v_mfma_f32_16x16x32_bf16 v[48:51], v[230:233], v[196:199], v[48:51]
	s_waitcnt lgkmcnt(4)
	v_mfma_f32_16x16x32_bf16 v[20:23], v[234:237], v[188:191], v[20:23]
	v_mfma_f32_16x16x32_bf16 v[52:55], v[234:237], v[196:199], v[52:55]
	s_waitcnt lgkmcnt(2)
	v_mfma_f32_16x16x32_bf16 v[24:27], v[238:241], v[188:191], v[24:27]
	v_mfma_f32_16x16x32_bf16 v[56:59], v[238:241], v[196:199], v[56:59]
	s_waitcnt lgkmcnt(0)
	v_mfma_f32_16x16x32_bf16 v[28:31], v[242:245], v[188:191], v[28:31]
	v_mfma_f32_16x16x32_bf16 v[60:63], v[242:245], v[196:199], v[60:63]
	s_waitcnt lgkmcnt(0)
	s_waitcnt vmcnt(0)
	s_barrier
; __device__ __forceinline__ int crow(int r, int hi) { return (r & 3) + 8 * (r >> 2) + 4 * hi; }
;     ...
;   if (hi == 0) li_l[r32] = l_reg; asm volatile("s_waitcnt lgkmcnt(0)" ::: "memory");
;   if constexpr (MODE == 1) { if (hi == 0) lse_out[(long)(wid * QBLK + r32) * lse_stride] = m_reg * SCALE + __logf(l_reg); }
;   float rli[16];
; #pragma unroll
;   for (int r = 0; r < 16; ++r) rli[r] = __builtin_amdgcn_rcpf(li_l[crow(r, hi)]);
;   bf16* Ow = Ob + (long)(wid * QBLK) * ldo;
; #pragma unroll
;   for (int r = 0; r < 16; ++r) { const int orow = crow(r, hi);
; #pragma unroll
;     for (int d0 = 0; d0 < 4; ++d0) Ow[(long)orow * ldo + d0 * 32 + r32] = __float2bfloat16(o[d0][r] * rli[r]); }
;   __syncthreads();
	s_setprio 0
	v_and_b32_e32 v64, 63, v218
	v_lshlrev_b32_e32 v64, 2, v64
	v_xor_b32_e32 v65, 64, v64
	v_xor_b32_e32 v66, 0x80, v64
	ds_bpermute_b32 v67, v65, v169
	s_waitcnt lgkmcnt(0)
	v_add_f32_e32 v169, v169, v67
	ds_bpermute_b32 v67, v66, v169
	s_waitcnt lgkmcnt(0)
	v_add_f32_e32 v169, v169, v67
	v_rcp_f32_e32 v169, v169
	ds_bpermute_b32 v67, v65, v222
	s_waitcnt lgkmcnt(0)
	v_add_f32_e32 v222, v222, v67
	ds_bpermute_b32 v67, v66, v222
	s_waitcnt lgkmcnt(0)
	v_add_f32_e32 v222, v222, v67
	v_rcp_f32_e32 v222, v222
	s_lshl_b64 s[0:1], s[20:21], 12
	s_add_u32 s0, s24, s0
	s_addc_u32 s1, s25, s1
	s_lshl_b32 s2, s14, 1
	s_add_u32 s2, s0, s2
	s_addc_u32 s3, s1, 0
	s_ashr_i32 s39, s38, 31
	s_lshl_b64 s[0:1], s[38:39], 12
	s_add_u32 s0, s2, s0
	s_addc_u32 s1, s3, s1
	v_and_b32_e32 v64, 63, v218
	v_and_b32_e32 v65, 15, v64
	v_lshrrev_b32_e32 v66, 4, v64
	v_lshlrev_b32_e32 v66, 3, v66
	v_lshl_or_b32 v68, v65, 12, v66
	v_add_u32_e32 v69, 0x10000, v68
	v_mul_f32_e32 v0, v0, v169
	v_mul_f32_e32 v1, v1, v169
	v_mul_f32_e32 v2, v2, v169
	v_mul_f32_e32 v3, v3, v169
	v_cvt_pk_bf16_f32 v130, v0, v1
	v_cvt_pk_bf16_f32 v131, v2, v3
	global_store_dwordx2 v68, v[130:131], s[0:1] offset:0
	v_mul_f32_e32 v4, v4, v169
	v_mul_f32_e32 v5, v5, v169
	v_mul_f32_e32 v6, v6, v169
	v_mul_f32_e32 v7, v7, v169
	v_cvt_pk_bf16_f32 v132, v4, v5
	v_cvt_pk_bf16_f32 v133, v6, v7
	global_store_dwordx2 v68, v[132:133], s[0:1] offset:32
	v_mul_f32_e32 v8, v8, v169
	v_mul_f32_e32 v9, v9, v169
	v_mul_f32_e32 v10, v10, v169
	v_mul_f32_e32 v11, v11, v169
	v_cvt_pk_bf16_f32 v134, v8, v9
	v_cvt_pk_bf16_f32 v135, v10, v11
	global_store_dwordx2 v68, v[134:135], s[0:1] offset:64
	v_mul_f32_e32 v12, v12, v169
	v_mul_f32_e32 v13, v13, v169
	v_mul_f32_e32 v14, v14, v169
	v_mul_f32_e32 v15, v15, v169
	v_cvt_pk_bf16_f32 v136, v12, v13
	v_cvt_pk_bf16_f32 v137, v14, v15
	global_store_dwordx2 v68, v[136:137], s[0:1] offset:96
	v_mul_f32_e32 v16, v16, v169
	v_mul_f32_e32 v17, v17, v169
	v_mul_f32_e32 v18, v18, v169
	v_mul_f32_e32 v19, v19, v169
	v_cvt_pk_bf16_f32 v138, v16, v17
	v_cvt_pk_bf16_f32 v139, v18, v19
	global_store_dwordx2 v68, v[138:139], s[0:1] offset:128
	v_mul_f32_e32 v20, v20, v169
	v_mul_f32_e32 v21, v21, v169
	v_mul_f32_e32 v22, v22, v169
	v_mul_f32_e32 v23, v23, v169
	v_cvt_pk_bf16_f32 v140, v20, v21
	v_cvt_pk_bf16_f32 v141, v22, v23
	global_store_dwordx2 v68, v[140:141], s[0:1] offset:160
	v_mul_f32_e32 v24, v24, v169
	v_mul_f32_e32 v25, v25, v169
	v_mul_f32_e32 v26, v26, v169
	v_mul_f32_e32 v27, v27, v169
	v_cvt_pk_bf16_f32 v142, v24, v25
	v_cvt_pk_bf16_f32 v143, v26, v27
	global_store_dwordx2 v68, v[142:143], s[0:1] offset:192
	v_mul_f32_e32 v28, v28, v169
	v_mul_f32_e32 v29, v29, v169
	v_mul_f32_e32 v30, v30, v169
	v_mul_f32_e32 v31, v31, v169
	v_cvt_pk_bf16_f32 v144, v28, v29
	v_cvt_pk_bf16_f32 v145, v30, v31
	global_store_dwordx2 v68, v[144:145], s[0:1] offset:224
	v_mul_f32_e32 v32, v32, v222
	v_mul_f32_e32 v33, v33, v222
	v_mul_f32_e32 v34, v34, v222
	v_mul_f32_e32 v35, v35, v222
	v_cvt_pk_bf16_f32 v130, v32, v33
	v_cvt_pk_bf16_f32 v131, v34, v35
	global_store_dwordx2 v69, v[130:131], s[0:1] offset:0
	v_mul_f32_e32 v36, v36, v222
	v_mul_f32_e32 v37, v37, v222
	v_mul_f32_e32 v38, v38, v222
	v_mul_f32_e32 v39, v39, v222
	v_cvt_pk_bf16_f32 v132, v36, v37
	v_cvt_pk_bf16_f32 v133, v38, v39
	global_store_dwordx2 v69, v[132:133], s[0:1] offset:32
	v_mul_f32_e32 v40, v40, v222
	v_mul_f32_e32 v41, v41, v222
	v_mul_f32_e32 v42, v42, v222
	v_mul_f32_e32 v43, v43, v222
	v_cvt_pk_bf16_f32 v134, v40, v41
	v_cvt_pk_bf16_f32 v135, v42, v43
	global_store_dwordx2 v69, v[134:135], s[0:1] offset:64
	v_mul_f32_e32 v44, v44, v222
	v_mul_f32_e32 v45, v45, v222
	v_mul_f32_e32 v46, v46, v222
	v_mul_f32_e32 v47, v47, v222
	v_cvt_pk_bf16_f32 v136, v44, v45
	v_cvt_pk_bf16_f32 v137, v46, v47
	global_store_dwordx2 v69, v[136:137], s[0:1] offset:96
	v_mul_f32_e32 v48, v48, v222
	v_mul_f32_e32 v49, v49, v222
	v_mul_f32_e32 v50, v50, v222
	v_mul_f32_e32 v51, v51, v222
	v_cvt_pk_bf16_f32 v138, v48, v49
	v_cvt_pk_bf16_f32 v139, v50, v51
	global_store_dwordx2 v69, v[138:139], s[0:1] offset:128
	v_mul_f32_e32 v52, v52, v222
	v_mul_f32_e32 v53, v53, v222
	v_mul_f32_e32 v54, v54, v222
	v_mul_f32_e32 v55, v55, v222
	v_cvt_pk_bf16_f32 v140, v52, v53
	v_cvt_pk_bf16_f32 v141, v54, v55
	global_store_dwordx2 v69, v[140:141], s[0:1] offset:160
	v_mul_f32_e32 v56, v56, v222
	v_mul_f32_e32 v57, v57, v222
	v_mul_f32_e32 v58, v58, v222
	v_mul_f32_e32 v59, v59, v222
	v_cvt_pk_bf16_f32 v142, v56, v57
	v_cvt_pk_bf16_f32 v143, v58, v59
	global_store_dwordx2 v69, v[142:143], s[0:1] offset:192
	v_mul_f32_e32 v60, v60, v222
	v_mul_f32_e32 v61, v61, v222
	v_mul_f32_e32 v62, v62, v222
	v_mul_f32_e32 v63, v63, v222
	v_cvt_pk_bf16_f32 v144, v60, v61
	v_cvt_pk_bf16_f32 v145, v62, v63
	global_store_dwordx2 v69, v[144:145], s[0:1] offset:224
	v_lshlrev_b32_e32 v164, 4, v229
	v_mov_b32_e32 v165, 0
	s_mov_b32 s50, -1
	s_barrier
	s_branch .LBB0_478
